# K-loop LDS-DMA loads converted to SADDR form (SGPR base + 32-bit VGPR offset), removing 100 per-iteration 64-bit VALU address adds across the 7 GEMM loops; on top of R6
# speedup vs baseline: 1.0127x; 1.0127x over previous
.Ldefbar_skip_0:
.LBB0_904:
	s_add_i32 s69, s8, 2
	s_add_u32 s0, s52, 0xfff80080
	s_addc_u32 s1, s53, -1
	s_add_i32 s70, 0, 0x10000
	s_cmp_eq_u32 s66, s8
	s_cselect_b32 s59, s41, s1
	s_cselect_b32 s58, s45, s0
	s_cselect_b32 s9, s43, s68
	s_cselect_b32 s8, s65, s67
	s_add_i32 s0, 0, 0x14000
	v_add_u32_e32 v156, s70, v141
	v_add_u32_e32 v172, s0, v141
	ds_read_b128 v[144:147], v156
	ds_read_b128 v[148:151], v156 offset:1024
	ds_read_b128 v[152:155], v156 offset:2048
	ds_read_b128 v[156:159], v156 offset:3072
	ds_read_b128 v[160:163], v172
	ds_read_b128 v[164:167], v172 offset:1024
	ds_read_b128 v[168:171], v172 offset:2048
	ds_read_b128 v[172:175], v172 offset:3072
	s_add_i32 m0, s27, 0xc000
	ds_read_b128 v[176:179], v143
	ds_read_b128 v[180:183], v143 offset:1024
	ds_read_b128 v[184:187], v143 offset:2048
	ds_read_b128 v[188:191], v143 offset:3072
	ds_read_b128 v[192:195], v143 offset:4096
	ds_read_b128 v[202:205], v143 offset:5120
	ds_read_b128 v[206:209], v143 offset:6144
	ds_read_b128 v[210:213], v143 offset:7168
	global_load_lds_dwordx4 v138, s[52:53]
	s_add_i32 m0, s27, 0xe000
	s_nop 0
	global_load_lds_dwordx4 v136, s[52:53]
	s_waitcnt vmcnt(8)
	s_waitcnt lgkmcnt(0)
	s_setprio 1
	s_barrier
	v_mfma_f32_16x16x32_bf16 v[126:129], v[144:147], v[176:179], v[126:129]
	v_mfma_f32_16x16x32_bf16 v[118:121], v[152:155], v[176:179], v[118:121]
	v_mfma_f32_16x16x32_bf16 v[110:113], v[144:147], v[184:187], v[110:113]
	v_mfma_f32_16x16x32_bf16 v[102:105], v[152:155], v[184:187], v[102:105]
	v_mfma_f32_16x16x32_bf16 v[94:97], v[144:147], v[192:195], v[94:97]
	v_mfma_f32_16x16x32_bf16 v[86:89], v[152:155], v[192:195], v[86:89]
	v_mfma_f32_16x16x32_bf16 v[78:81], v[144:147], v[206:209], v[78:81]
	v_mfma_f32_16x16x32_bf16 v[70:73], v[152:155], v[206:209], v[70:73]
	v_mfma_f32_16x16x32_bf16 v[126:129], v[148:151], v[180:183], v[126:129]
	v_mfma_f32_16x16x32_bf16 v[118:121], v[156:159], v[180:183], v[118:121]
	v_mfma_f32_16x16x32_bf16 v[110:113], v[148:151], v[188:191], v[110:113]
	v_mfma_f32_16x16x32_bf16 v[102:105], v[156:159], v[188:191], v[102:105]
	v_mfma_f32_16x16x32_bf16 v[94:97], v[148:151], v[202:205], v[94:97]
	v_mfma_f32_16x16x32_bf16 v[86:89], v[156:159], v[202:205], v[86:89]
	v_mfma_f32_16x16x32_bf16 v[78:81], v[148:151], v[210:213], v[78:81]
	v_mfma_f32_16x16x32_bf16 v[70:73], v[156:159], v[210:213], v[70:73]
	v_mfma_f32_16x16x32_bf16 v[122:125], v[160:163], v[176:179], v[122:125]
	v_mfma_f32_16x16x32_bf16 v[114:117], v[168:171], v[176:179], v[114:117]
	v_mfma_f32_16x16x32_bf16 v[106:109], v[160:163], v[184:187], v[106:109]
	v_mfma_f32_16x16x32_bf16 v[98:101], v[168:171], v[184:187], v[98:101]
	v_mfma_f32_16x16x32_bf16 v[90:93], v[160:163], v[192:195], v[90:93]
	v_mfma_f32_16x16x32_bf16 v[82:85], v[168:171], v[192:195], v[82:85]
	v_mfma_f32_16x16x32_bf16 v[74:77], v[160:163], v[206:209], v[74:77]
	v_mfma_f32_16x16x32_bf16 v[66:69], v[168:171], v[206:209], v[66:69]
	v_mfma_f32_16x16x32_bf16 v[122:125], v[164:167], v[180:183], v[122:125]
	v_mfma_f32_16x16x32_bf16 v[114:117], v[172:175], v[180:183], v[114:117]
	v_mfma_f32_16x16x32_bf16 v[106:109], v[164:167], v[188:191], v[106:109]
	v_mfma_f32_16x16x32_bf16 v[98:101], v[172:175], v[188:191], v[98:101]
	v_mfma_f32_16x16x32_bf16 v[90:93], v[164:167], v[202:205], v[90:93]
	v_mfma_f32_16x16x32_bf16 v[82:85], v[172:175], v[202:205], v[82:85]
	v_mfma_f32_16x16x32_bf16 v[74:77], v[164:167], v[210:213], v[74:77]
	v_mfma_f32_16x16x32_bf16 v[66:69], v[172:175], v[210:213], v[66:69]
	s_barrier
	s_setprio 0
	s_add_i32 s1, s70, s26
	s_add_u32 s98, s8, s16
	s_addc_u32 s99, s9, s17
	s_mov_b32 m0, s1
	ds_read_b128 v[176:179], v143 offset:16384
	ds_read_b128 v[180:183], v143 offset:17408
	ds_read_b128 v[184:187], v143 offset:18432
	ds_read_b128 v[188:191], v143 offset:19456
	ds_read_b128 v[192:195], v143 offset:20480
	ds_read_b128 v[202:205], v143 offset:21504
	ds_read_b128 v[206:209], v143 offset:22528
	ds_read_b128 v[210:213], v143 offset:23552
	global_load_lds_dwordx4 v196, s[8:9]
	s_add_i32 m0, s1, 0x2000
	s_add_u32 s70, s8, 0x80000
	s_addc_u32 s71, s9, 0
	s_add_i32 s0, s0, s26
	global_load_lds_dwordx4 v130, s[8:9]
	s_mov_b32 m0, s0
	s_nop 0
	global_load_lds_dwordx4 v196, s[70:71]
	s_add_i32 m0, s0, 0x2000
	s_nop 0
	global_load_lds_dwordx4 v130, s[70:71]
	s_add_u32 s78, s58, s16
	s_addc_u32 s79, s59, s17
	s_mov_b32 m0, s27
	s_nop 0
	global_load_lds_dwordx4 v134, s[58:59]
	s_mov_b32 m0, s28
	s_nop 0
	global_load_lds_dwordx4 v132, s[58:59]
	s_waitcnt vmcnt(8)
	s_waitcnt lgkmcnt(0)
	s_setprio 1
	s_barrier
	v_mfma_f32_16x16x32_bf16 v[62:65], v[144:147], v[176:179], v[62:65]
	v_mfma_f32_16x16x32_bf16 v[54:57], v[152:155], v[176:179], v[54:57]
	v_mfma_f32_16x16x32_bf16 v[46:49], v[144:147], v[184:187], v[46:49]
	v_mfma_f32_16x16x32_bf16 v[38:41], v[152:155], v[184:187], v[38:41]
	v_mfma_f32_16x16x32_bf16 v[30:33], v[144:147], v[192:195], v[30:33]
	v_mfma_f32_16x16x32_bf16 v[22:25], v[152:155], v[192:195], v[22:25]
	v_mfma_f32_16x16x32_bf16 v[14:17], v[144:147], v[206:209], v[14:17]
	v_mfma_f32_16x16x32_bf16 v[6:9], v[152:155], v[206:209], v[6:9]
	v_mfma_f32_16x16x32_bf16 v[62:65], v[148:151], v[180:183], v[62:65]
	v_mfma_f32_16x16x32_bf16 v[54:57], v[156:159], v[180:183], v[54:57]
	v_mfma_f32_16x16x32_bf16 v[46:49], v[148:151], v[188:191], v[46:49]
	v_mfma_f32_16x16x32_bf16 v[38:41], v[156:159], v[188:191], v[38:41]
	v_mfma_f32_16x16x32_bf16 v[30:33], v[148:151], v[202:205], v[30:33]
	v_mfma_f32_16x16x32_bf16 v[22:25], v[156:159], v[202:205], v[22:25]
	v_mfma_f32_16x16x32_bf16 v[14:17], v[148:151], v[210:213], v[14:17]
	v_mfma_f32_16x16x32_bf16 v[6:9], v[156:159], v[210:213], v[6:9]
	v_mfma_f32_16x16x32_bf16 v[58:61], v[160:163], v[176:179], v[58:61]
	v_mfma_f32_16x16x32_bf16 v[50:53], v[168:171], v[176:179], v[50:53]
	v_mfma_f32_16x16x32_bf16 v[42:45], v[160:163], v[184:187], v[42:45]
	v_mfma_f32_16x16x32_bf16 v[34:37], v[168:171], v[184:187], v[34:37]
	v_mfma_f32_16x16x32_bf16 v[26:29], v[160:163], v[192:195], v[26:29]
	v_mfma_f32_16x16x32_bf16 v[18:21], v[168:171], v[192:195], v[18:21]
	v_mfma_f32_16x16x32_bf16 v[10:13], v[160:163], v[206:209], v[10:13]
	v_mfma_f32_16x16x32_bf16 v[2:5], v[168:171], v[206:209], v[2:5]
	v_mfma_f32_16x16x32_bf16 v[58:61], v[164:167], v[180:183], v[58:61]
	v_mfma_f32_16x16x32_bf16 v[50:53], v[172:175], v[180:183], v[50:53]
	v_mfma_f32_16x16x32_bf16 v[42:45], v[164:167], v[188:191], v[42:45]
	v_mfma_f32_16x16x32_bf16 v[34:37], v[172:175], v[188:191], v[34:37]
	v_mfma_f32_16x16x32_bf16 v[26:29], v[164:167], v[202:205], v[26:29]
	v_mfma_f32_16x16x32_bf16 v[18:21], v[172:175], v[202:205], v[18:21]
	v_mfma_f32_16x16x32_bf16 v[10:13], v[164:167], v[210:213], v[10:13]
	v_mfma_f32_16x16x32_bf16 v[2:5], v[172:175], v[210:213], v[2:5]
	s_barrier
	s_setprio 0
	s_add_i32 s0, 0, 0x18000
	s_add_i32 s1, 0, 0x1c000
	v_add_u32_e32 v156, s0, v141
	v_add_u32_e32 v172, s1, v141
	ds_read_b128 v[144:147], v156
	ds_read_b128 v[148:151], v156 offset:1024
	ds_read_b128 v[152:155], v156 offset:2048
	ds_read_b128 v[156:159], v156 offset:3072
	ds_read_b128 v[160:163], v172
	ds_read_b128 v[164:167], v172 offset:1024
	ds_read_b128 v[168:171], v172 offset:2048
	ds_read_b128 v[172:175], v172 offset:3072
	s_add_u32 s58, s58, 0x80000
	s_addc_u32 s59, s59, 0
	s_mov_b32 m0, s29
	ds_read_b128 v[176:179], v143 offset:32768
	ds_read_b128 v[180:183], v143 offset:33792
	ds_read_b128 v[184:187], v143 offset:34816
	ds_read_b128 v[188:191], v143 offset:35840
	ds_read_b128 v[192:195], v143 offset:36864
	ds_read_b128 v[202:205], v143 offset:37888
	ds_read_b128 v[206:209], v143 offset:38912
	ds_read_b128 v[210:213], v143 offset:39936
	global_load_lds_dwordx4 v134, s[58:59]
	s_mov_b32 m0, s30
	s_nop 0
	global_load_lds_dwordx4 v132, s[58:59]
	s_waitcnt vmcnt(8)
	s_waitcnt lgkmcnt(0)
	s_setprio 1
	s_barrier
	v_mfma_f32_16x16x32_bf16 v[126:129], v[144:147], v[176:179], v[126:129]
	v_mfma_f32_16x16x32_bf16 v[118:121], v[152:155], v[176:179], v[118:121]
	v_mfma_f32_16x16x32_bf16 v[110:113], v[144:147], v[184:187], v[110:113]
	v_mfma_f32_16x16x32_bf16 v[102:105], v[152:155], v[184:187], v[102:105]
	v_mfma_f32_16x16x32_bf16 v[94:97], v[144:147], v[192:195], v[94:97]
	v_mfma_f32_16x16x32_bf16 v[86:89], v[152:155], v[192:195], v[86:89]
	v_mfma_f32_16x16x32_bf16 v[78:81], v[144:147], v[206:209], v[78:81]
	v_mfma_f32_16x16x32_bf16 v[70:73], v[152:155], v[206:209], v[70:73]
	v_mfma_f32_16x16x32_bf16 v[126:129], v[148:151], v[180:183], v[126:129]
	v_mfma_f32_16x16x32_bf16 v[118:121], v[156:159], v[180:183], v[118:121]
	v_mfma_f32_16x16x32_bf16 v[110:113], v[148:151], v[188:191], v[110:113]
	v_mfma_f32_16x16x32_bf16 v[102:105], v[156:159], v[188:191], v[102:105]
	v_mfma_f32_16x16x32_bf16 v[94:97], v[148:151], v[202:205], v[94:97]
	v_mfma_f32_16x16x32_bf16 v[86:89], v[156:159], v[202:205], v[86:89]
	v_mfma_f32_16x16x32_bf16 v[78:81], v[148:151], v[210:213], v[78:81]
	v_mfma_f32_16x16x32_bf16 v[70:73], v[156:159], v[210:213], v[70:73]
	v_mfma_f32_16x16x32_bf16 v[122:125], v[160:163], v[176:179], v[122:125]
	v_mfma_f32_16x16x32_bf16 v[114:117], v[168:171], v[176:179], v[114:117]
	v_mfma_f32_16x16x32_bf16 v[106:109], v[160:163], v[184:187], v[106:109]
	v_mfma_f32_16x16x32_bf16 v[98:101], v[168:171], v[184:187], v[98:101]
	v_mfma_f32_16x16x32_bf16 v[90:93], v[160:163], v[192:195], v[90:93]
	v_mfma_f32_16x16x32_bf16 v[82:85], v[168:171], v[192:195], v[82:85]
	v_mfma_f32_16x16x32_bf16 v[74:77], v[160:163], v[206:209], v[74:77]
	v_mfma_f32_16x16x32_bf16 v[66:69], v[168:171], v[206:209], v[66:69]
	v_mfma_f32_16x16x32_bf16 v[122:125], v[164:167], v[180:183], v[122:125]
	v_mfma_f32_16x16x32_bf16 v[114:117], v[172:175], v[180:183], v[114:117]
	v_mfma_f32_16x16x32_bf16 v[106:109], v[164:167], v[188:191], v[106:109]
	v_mfma_f32_16x16x32_bf16 v[98:101], v[172:175], v[188:191], v[98:101]
	v_mfma_f32_16x16x32_bf16 v[90:93], v[164:167], v[202:205], v[90:93]
	v_mfma_f32_16x16x32_bf16 v[82:85], v[172:175], v[202:205], v[82:85]
	v_mfma_f32_16x16x32_bf16 v[74:77], v[164:167], v[210:213], v[74:77]
	v_mfma_f32_16x16x32_bf16 v[66:69], v[172:175], v[210:213], v[66:69]
	s_barrier
	s_setprio 0
	s_add_i32 s0, s0, s26
	s_mov_b32 m0, s0
	ds_read_b128 v[176:179], v143 offset:49152
	ds_read_b128 v[180:183], v143 offset:50176
	ds_read_b128 v[184:187], v143 offset:51200
	ds_read_b128 v[188:191], v143 offset:52224
	ds_read_b128 v[192:195], v143 offset:53248
	ds_read_b128 v[202:205], v143 offset:54272
	ds_read_b128 v[206:209], v143 offset:55296
	ds_read_b128 v[210:213], v143 offset:56320
	global_load_lds_dwordx4 v196, s[98:99]
	s_add_i32 m0, s0, 0x2000
	s_add_u32 s8, s8, 0x80080
	s_addc_u32 s9, s9, 0
	s_add_i32 s0, s1, s26
	global_load_lds_dwordx4 v130, s[98:99]
	s_mov_b32 m0, s0
	s_nop 0
	global_load_lds_dwordx4 v196, s[8:9]
	s_add_i32 m0, s0, 0x2000
	s_nop 0
	global_load_lds_dwordx4 v130, s[8:9]
	s_mov_b32 m0, s31
	s_nop 0
	global_load_lds_dwordx4 v134, s[78:79]
	s_mov_b32 m0, s34
	s_nop 0
	global_load_lds_dwordx4 v132, s[78:79]
	s_waitcnt vmcnt(8)
	s_waitcnt lgkmcnt(0)
	s_setprio 1
	s_barrier
	v_mfma_f32_16x16x32_bf16 v[62:65], v[144:147], v[176:179], v[62:65]
	v_mfma_f32_16x16x32_bf16 v[54:57], v[152:155], v[176:179], v[54:57]
	v_mfma_f32_16x16x32_bf16 v[46:49], v[144:147], v[184:187], v[46:49]
	v_mfma_f32_16x16x32_bf16 v[38:41], v[152:155], v[184:187], v[38:41]
	v_mfma_f32_16x16x32_bf16 v[30:33], v[144:147], v[192:195], v[30:33]
	v_mfma_f32_16x16x32_bf16 v[22:25], v[152:155], v[192:195], v[22:25]
	v_mfma_f32_16x16x32_bf16 v[14:17], v[144:147], v[206:209], v[14:17]
	v_mfma_f32_16x16x32_bf16 v[6:9], v[152:155], v[206:209], v[6:9]
	v_mfma_f32_16x16x32_bf16 v[62:65], v[148:151], v[180:183], v[62:65]
	v_mfma_f32_16x16x32_bf16 v[54:57], v[156:159], v[180:183], v[54:57]
	v_mfma_f32_16x16x32_bf16 v[46:49], v[148:151], v[188:191], v[46:49]
	v_mfma_f32_16x16x32_bf16 v[38:41], v[156:159], v[188:191], v[38:41]
	v_mfma_f32_16x16x32_bf16 v[30:33], v[148:151], v[202:205], v[30:33]
	v_mfma_f32_16x16x32_bf16 v[22:25], v[156:159], v[202:205], v[22:25]
	v_mfma_f32_16x16x32_bf16 v[14:17], v[148:151], v[210:213], v[14:17]
	v_mfma_f32_16x16x32_bf16 v[6:9], v[156:159], v[210:213], v[6:9]
	v_mfma_f32_16x16x32_bf16 v[58:61], v[160:163], v[176:179], v[58:61]
	v_mfma_f32_16x16x32_bf16 v[50:53], v[168:171], v[176:179], v[50:53]
	v_mfma_f32_16x16x32_bf16 v[42:45], v[160:163], v[184:187], v[42:45]
	v_mfma_f32_16x16x32_bf16 v[34:37], v[168:171], v[184:187], v[34:37]
	v_mfma_f32_16x16x32_bf16 v[26:29], v[160:163], v[192:195], v[26:29]
	v_mfma_f32_16x16x32_bf16 v[18:21], v[168:171], v[192:195], v[18:21]
	v_mfma_f32_16x16x32_bf16 v[10:13], v[160:163], v[206:209], v[10:13]
	v_mfma_f32_16x16x32_bf16 v[2:5], v[168:171], v[206:209], v[2:5]
	v_mfma_f32_16x16x32_bf16 v[58:61], v[164:167], v[180:183], v[58:61]
	v_mfma_f32_16x16x32_bf16 v[50:53], v[172:175], v[180:183], v[50:53]
	v_mfma_f32_16x16x32_bf16 v[42:45], v[164:167], v[188:191], v[42:45]
	v_mfma_f32_16x16x32_bf16 v[34:37], v[172:175], v[188:191], v[34:37]
	v_mfma_f32_16x16x32_bf16 v[26:29], v[164:167], v[202:205], v[26:29]
	v_mfma_f32_16x16x32_bf16 v[18:21], v[172:175], v[202:205], v[18:21]
	v_mfma_f32_16x16x32_bf16 v[10:13], v[164:167], v[210:213], v[10:13]
	v_mfma_f32_16x16x32_bf16 v[2:5], v[172:175], v[210:213], v[2:5]
	s_barrier
	s_setprio 0
	s_add_u32 s67, s67, 0x100
	s_addc_u32 s68, s68, 0
	s_add_u32 s52, s52, 0x100
	s_addc_u32 s53, s53, 0
	s_cmp_ge_i32 s69, s62
	s_mov_b32 s8, s69
	s_cbranch_scc0 .LBB0_904
	s_and_b64 vcc, exec, s[38:39]
	s_cbranch_vccz .LBB0_907
	s_barrier

.Ldefbar_skip_1:
.LBB0_987:
	s_add_i32 s72, s50, 2
	s_add_u32 s8, s48, 0x100
	s_addc_u32 s9, s49, 0
	s_add_i32 s0, 0, 0x10000
	s_cmp_eq_u32 s41, s50
	s_cselect_b32 s53, s45, s9
	s_cselect_b32 s52, s44, s8
	s_cselect_b32 s51, s47, s71
	s_cselect_b32 s50, s46, s70
	s_add_i32 s1, 0, 0x14000
	v_add_u32_e32 v142, s0, v188
	v_add_u32_e32 v172, s1, v188
	ds_read_b128 v[130:133], v142
	ds_read_b128 v[134:137], v142 offset:1024
	ds_read_b128 v[138:141], v142 offset:2048
	ds_read_b128 v[142:145], v142 offset:3072
	ds_read_b128 v[146:149], v172
	ds_read_b128 v[164:167], v172 offset:1024
	ds_read_b128 v[168:171], v172 offset:2048
	ds_read_b128 v[172:175], v172 offset:3072
	v_lshl_add_u64 v[194:195], s[48:49], 0, v[162:163]
	s_add_i32 m0, s27, 0xc000
	ds_read_b128 v[176:179], v189
	ds_read_b128 v[180:183], v189 offset:1024
	ds_read_b128 v[184:187], v189 offset:2048
	ds_read_b128 v[190:193], v189 offset:3072
	ds_read_b128 v[202:205], v189 offset:4096
	ds_read_b128 v[206:209], v189 offset:5120
	ds_read_b128 v[210:213], v189 offset:6144
	ds_read_b128 v[214:217], v189 offset:7168
	global_load_lds_dwordx4 v[194:195], off
	v_lshl_add_u64 v[194:195], s[48:49], 0, v[160:161]
	s_add_i32 m0, s27, 0xe000
	s_nop 0
	global_load_lds_dwordx4 v[194:195], off
	s_waitcnt vmcnt(8)
	s_waitcnt lgkmcnt(0)
	s_setprio 1
	s_barrier
	v_mfma_f32_16x16x32_bf16 v[126:129], v[130:133], v[176:179], v[126:129]
	v_mfma_f32_16x16x32_bf16 v[122:125], v[138:141], v[176:179], v[122:125]
	v_mfma_f32_16x16x32_bf16 v[110:113], v[130:133], v[184:187], v[110:113]
	v_mfma_f32_16x16x32_bf16 v[106:109], v[138:141], v[184:187], v[106:109]
	v_mfma_f32_16x16x32_bf16 v[98:101], v[130:133], v[202:205], v[98:101]
	v_mfma_f32_16x16x32_bf16 v[90:93], v[138:141], v[202:205], v[90:93]
	v_mfma_f32_16x16x32_bf16 v[82:85], v[130:133], v[210:213], v[82:85]
	v_mfma_f32_16x16x32_bf16 v[74:77], v[138:141], v[210:213], v[74:77]
	v_mfma_f32_16x16x32_bf16 v[126:129], v[134:137], v[180:183], v[126:129]
	v_mfma_f32_16x16x32_bf16 v[122:125], v[142:145], v[180:183], v[122:125]
	v_mfma_f32_16x16x32_bf16 v[110:113], v[134:137], v[190:193], v[110:113]
	v_mfma_f32_16x16x32_bf16 v[106:109], v[142:145], v[190:193], v[106:109]
	v_mfma_f32_16x16x32_bf16 v[98:101], v[134:137], v[206:209], v[98:101]
	v_mfma_f32_16x16x32_bf16 v[90:93], v[142:145], v[206:209], v[90:93]
	v_mfma_f32_16x16x32_bf16 v[82:85], v[134:137], v[214:217], v[82:85]
	v_mfma_f32_16x16x32_bf16 v[74:77], v[142:145], v[214:217], v[74:77]
	v_mfma_f32_16x16x32_bf16 v[118:121], v[146:149], v[176:179], v[118:121]
	v_mfma_f32_16x16x32_bf16 v[114:117], v[168:171], v[176:179], v[114:117]
	v_mfma_f32_16x16x32_bf16 v[102:105], v[146:149], v[184:187], v[102:105]
	v_mfma_f32_16x16x32_bf16 v[94:97], v[168:171], v[184:187], v[94:97]
	v_mfma_f32_16x16x32_bf16 v[86:89], v[146:149], v[202:205], v[86:89]
	v_mfma_f32_16x16x32_bf16 v[78:81], v[168:171], v[202:205], v[78:81]
	v_mfma_f32_16x16x32_bf16 v[70:73], v[146:149], v[210:213], v[70:73]
	v_mfma_f32_16x16x32_bf16 v[66:69], v[168:171], v[210:213], v[66:69]
	v_mfma_f32_16x16x32_bf16 v[118:121], v[164:167], v[180:183], v[118:121]
	v_mfma_f32_16x16x32_bf16 v[114:117], v[172:175], v[180:183], v[114:117]
	v_mfma_f32_16x16x32_bf16 v[102:105], v[164:167], v[190:193], v[102:105]
	v_mfma_f32_16x16x32_bf16 v[94:97], v[172:175], v[190:193], v[94:97]
	v_mfma_f32_16x16x32_bf16 v[86:89], v[164:167], v[206:209], v[86:89]
	v_mfma_f32_16x16x32_bf16 v[78:81], v[172:175], v[206:209], v[78:81]
	v_mfma_f32_16x16x32_bf16 v[70:73], v[164:167], v[214:217], v[70:73]
	v_mfma_f32_16x16x32_bf16 v[66:69], v[172:175], v[214:217], v[66:69]
	s_barrier
	s_setprio 0
	s_add_i32 s0, s0, s26
	s_add_u32 s98, s50, s16
	s_addc_u32 s99, s51, s17
	s_mov_b32 m0, s0
	ds_read_b128 v[176:179], v189 offset:16384
	ds_read_b128 v[180:183], v189 offset:17408
	ds_read_b128 v[184:187], v189 offset:18432
	ds_read_b128 v[190:193], v189 offset:19456
	ds_read_b128 v[202:205], v189 offset:20480
	ds_read_b128 v[206:209], v189 offset:21504
	ds_read_b128 v[210:213], v189 offset:22528
	ds_read_b128 v[214:217], v189 offset:23552
	global_load_lds_dwordx4 v196, s[50:51]
	s_add_i32 m0, s0, 0x2000
	s_add_u32 s48, s50, 0x158000
	s_addc_u32 s49, s51, 0
	s_add_i32 s0, s1, s26
	global_load_lds_dwordx4 v154, s[50:51]
	s_mov_b32 m0, s0
	s_nop 0
	global_load_lds_dwordx4 v196, s[48:49]
	s_add_i32 m0, s0, 0x2000
	s_nop 0
	global_load_lds_dwordx4 v154, s[48:49]
	s_add_u32 s78, s52, s16
	s_addc_u32 s79, s53, s17
	s_mov_b32 m0, s27
	s_nop 0
	global_load_lds_dwordx4 v150, s[52:53]
	s_mov_b32 m0, s28
	s_nop 0
	global_load_lds_dwordx4 v152, s[52:53]
	s_waitcnt vmcnt(8)
	s_waitcnt lgkmcnt(0)
	s_setprio 1
	s_barrier
	v_mfma_f32_16x16x32_bf16 v[62:65], v[130:133], v[176:179], v[62:65]
	v_mfma_f32_16x16x32_bf16 v[58:61], v[138:141], v[176:179], v[58:61]
	v_mfma_f32_16x16x32_bf16 v[50:53], v[130:133], v[184:187], v[50:53]
	v_mfma_f32_16x16x32_bf16 v[42:45], v[138:141], v[184:187], v[42:45]
	v_mfma_f32_16x16x32_bf16 v[34:37], v[130:133], v[202:205], v[34:37]
	v_mfma_f32_16x16x32_bf16 v[26:29], v[138:141], v[202:205], v[26:29]
	v_mfma_f32_16x16x32_bf16 v[18:21], v[130:133], v[210:213], v[18:21]
	v_mfma_f32_16x16x32_bf16 v[10:13], v[138:141], v[210:213], v[10:13]
	v_mfma_f32_16x16x32_bf16 v[62:65], v[134:137], v[180:183], v[62:65]
	v_mfma_f32_16x16x32_bf16 v[58:61], v[142:145], v[180:183], v[58:61]
	v_mfma_f32_16x16x32_bf16 v[50:53], v[134:137], v[190:193], v[50:53]
	v_mfma_f32_16x16x32_bf16 v[42:45], v[142:145], v[190:193], v[42:45]
	v_mfma_f32_16x16x32_bf16 v[34:37], v[134:137], v[206:209], v[34:37]
	v_mfma_f32_16x16x32_bf16 v[26:29], v[142:145], v[206:209], v[26:29]
	v_mfma_f32_16x16x32_bf16 v[18:21], v[134:137], v[214:217], v[18:21]
	v_mfma_f32_16x16x32_bf16 v[10:13], v[142:145], v[214:217], v[10:13]
	v_mfma_f32_16x16x32_bf16 v[54:57], v[146:149], v[176:179], v[54:57]
	v_mfma_f32_16x16x32_bf16 v[46:49], v[168:171], v[176:179], v[46:49]
	v_mfma_f32_16x16x32_bf16 v[38:41], v[146:149], v[184:187], v[38:41]
	v_mfma_f32_16x16x32_bf16 v[30:33], v[168:171], v[184:187], v[30:33]
	v_mfma_f32_16x16x32_bf16 v[22:25], v[146:149], v[202:205], v[22:25]
	v_mfma_f32_16x16x32_bf16 v[14:17], v[168:171], v[202:205], v[14:17]
	v_mfma_f32_16x16x32_bf16 v[6:9], v[146:149], v[210:213], v[6:9]
	v_mfma_f32_16x16x32_bf16 v[2:5], v[168:171], v[210:213], v[2:5]
	v_mfma_f32_16x16x32_bf16 v[54:57], v[164:167], v[180:183], v[54:57]
	v_mfma_f32_16x16x32_bf16 v[46:49], v[172:175], v[180:183], v[46:49]
	v_mfma_f32_16x16x32_bf16 v[38:41], v[164:167], v[190:193], v[38:41]
	v_mfma_f32_16x16x32_bf16 v[30:33], v[172:175], v[190:193], v[30:33]
	v_mfma_f32_16x16x32_bf16 v[22:25], v[164:167], v[206:209], v[22:25]
	v_mfma_f32_16x16x32_bf16 v[14:17], v[172:175], v[206:209], v[14:17]
	v_mfma_f32_16x16x32_bf16 v[6:9], v[164:167], v[214:217], v[6:9]
	v_mfma_f32_16x16x32_bf16 v[2:5], v[172:175], v[214:217], v[2:5]
	s_barrier
	s_setprio 0
	s_add_i32 s0, 0, 0x18000
	s_add_i32 s1, 0, 0x1c000
	v_add_u32_e32 v142, s0, v188
	v_add_u32_e32 v172, s1, v188
	ds_read_b128 v[130:133], v142
	ds_read_b128 v[134:137], v142 offset:1024
	ds_read_b128 v[138:141], v142 offset:2048
	ds_read_b128 v[142:145], v142 offset:3072
	ds_read_b128 v[146:149], v172
	ds_read_b128 v[164:167], v172 offset:1024
	ds_read_b128 v[168:171], v172 offset:2048
	ds_read_b128 v[172:175], v172 offset:3072
	s_add_u32 s48, s52, 0x158000
	s_addc_u32 s49, s53, 0
	s_mov_b32 m0, s29
	ds_read_b128 v[176:179], v189 offset:32768
	ds_read_b128 v[180:183], v189 offset:33792
	ds_read_b128 v[184:187], v189 offset:34816
	ds_read_b128 v[190:193], v189 offset:35840
	ds_read_b128 v[202:205], v189 offset:36864
	ds_read_b128 v[206:209], v189 offset:37888
	ds_read_b128 v[210:213], v189 offset:38912
	ds_read_b128 v[214:217], v189 offset:39936
	global_load_lds_dwordx4 v150, s[48:49]
	s_mov_b32 m0, s30
	s_nop 0
	global_load_lds_dwordx4 v152, s[48:49]
	s_waitcnt vmcnt(8)
	s_waitcnt lgkmcnt(0)
	s_setprio 1
	s_barrier
	v_mfma_f32_16x16x32_bf16 v[126:129], v[130:133], v[176:179], v[126:129]
	v_mfma_f32_16x16x32_bf16 v[122:125], v[138:141], v[176:179], v[122:125]
	v_mfma_f32_16x16x32_bf16 v[110:113], v[130:133], v[184:187], v[110:113]
	v_mfma_f32_16x16x32_bf16 v[106:109], v[138:141], v[184:187], v[106:109]
	v_mfma_f32_16x16x32_bf16 v[98:101], v[130:133], v[202:205], v[98:101]
	v_mfma_f32_16x16x32_bf16 v[90:93], v[138:141], v[202:205], v[90:93]
	v_mfma_f32_16x16x32_bf16 v[82:85], v[130:133], v[210:213], v[82:85]
	v_mfma_f32_16x16x32_bf16 v[74:77], v[138:141], v[210:213], v[74:77]
	v_mfma_f32_16x16x32_bf16 v[126:129], v[134:137], v[180:183], v[126:129]
	v_mfma_f32_16x16x32_bf16 v[122:125], v[142:145], v[180:183], v[122:125]
	v_mfma_f32_16x16x32_bf16 v[110:113], v[134:137], v[190:193], v[110:113]
	v_mfma_f32_16x16x32_bf16 v[106:109], v[142:145], v[190:193], v[106:109]
	v_mfma_f32_16x16x32_bf16 v[98:101], v[134:137], v[206:209], v[98:101]
	v_mfma_f32_16x16x32_bf16 v[90:93], v[142:145], v[206:209], v[90:93]
	v_mfma_f32_16x16x32_bf16 v[82:85], v[134:137], v[214:217], v[82:85]
	v_mfma_f32_16x16x32_bf16 v[74:77], v[142:145], v[214:217], v[74:77]
	v_mfma_f32_16x16x32_bf16 v[118:121], v[146:149], v[176:179], v[118:121]
	v_mfma_f32_16x16x32_bf16 v[114:117], v[168:171], v[176:179], v[114:117]
	v_mfma_f32_16x16x32_bf16 v[102:105], v[146:149], v[184:187], v[102:105]
	v_mfma_f32_16x16x32_bf16 v[94:97], v[168:171], v[184:187], v[94:97]
	v_mfma_f32_16x16x32_bf16 v[86:89], v[146:149], v[202:205], v[86:89]
	v_mfma_f32_16x16x32_bf16 v[78:81], v[168:171], v[202:205], v[78:81]
	v_mfma_f32_16x16x32_bf16 v[70:73], v[146:149], v[210:213], v[70:73]
	v_mfma_f32_16x16x32_bf16 v[66:69], v[168:171], v[210:213], v[66:69]
	v_mfma_f32_16x16x32_bf16 v[118:121], v[164:167], v[180:183], v[118:121]
	v_mfma_f32_16x16x32_bf16 v[114:117], v[172:175], v[180:183], v[114:117]
	v_mfma_f32_16x16x32_bf16 v[102:105], v[164:167], v[190:193], v[102:105]
	v_mfma_f32_16x16x32_bf16 v[94:97], v[172:175], v[190:193], v[94:97]
	v_mfma_f32_16x16x32_bf16 v[86:89], v[164:167], v[206:209], v[86:89]
	v_mfma_f32_16x16x32_bf16 v[78:81], v[172:175], v[206:209], v[78:81]
	v_mfma_f32_16x16x32_bf16 v[70:73], v[164:167], v[214:217], v[70:73]
	v_mfma_f32_16x16x32_bf16 v[66:69], v[172:175], v[214:217], v[66:69]
	s_barrier
	s_setprio 0
	s_add_i32 s0, s0, s26
	s_mov_b32 m0, s0
	ds_read_b128 v[176:179], v189 offset:49152
	ds_read_b128 v[180:183], v189 offset:50176
	ds_read_b128 v[184:187], v189 offset:51200
	ds_read_b128 v[190:193], v189 offset:52224
	ds_read_b128 v[202:205], v189 offset:53248
	ds_read_b128 v[206:209], v189 offset:54272
	ds_read_b128 v[210:213], v189 offset:55296
	ds_read_b128 v[214:217], v189 offset:56320
	global_load_lds_dwordx4 v196, s[98:99]
	s_add_i32 m0, s0, 0x2000
	s_add_u32 s48, s50, 0x158080
	s_addc_u32 s49, s51, 0
	s_add_i32 s0, s1, s26
	global_load_lds_dwordx4 v154, s[98:99]
	s_mov_b32 m0, s0
	s_nop 0
	global_load_lds_dwordx4 v196, s[48:49]
	s_add_i32 m0, s0, 0x2000
	s_nop 0
	global_load_lds_dwordx4 v154, s[48:49]
	s_mov_b32 m0, s35
	s_nop 0
	global_load_lds_dwordx4 v150, s[78:79]
	s_mov_b32 m0, s58
	s_nop 0
	global_load_lds_dwordx4 v152, s[78:79]
	s_waitcnt vmcnt(8)
	s_waitcnt lgkmcnt(0)
	s_setprio 1
	s_barrier
	v_mfma_f32_16x16x32_bf16 v[62:65], v[130:133], v[176:179], v[62:65]
	v_mfma_f32_16x16x32_bf16 v[58:61], v[138:141], v[176:179], v[58:61]
	v_mfma_f32_16x16x32_bf16 v[50:53], v[130:133], v[184:187], v[50:53]
	v_mfma_f32_16x16x32_bf16 v[42:45], v[138:141], v[184:187], v[42:45]
	v_mfma_f32_16x16x32_bf16 v[34:37], v[130:133], v[202:205], v[34:37]
	v_mfma_f32_16x16x32_bf16 v[26:29], v[138:141], v[202:205], v[26:29]
	v_mfma_f32_16x16x32_bf16 v[18:21], v[130:133], v[210:213], v[18:21]
	v_mfma_f32_16x16x32_bf16 v[10:13], v[138:141], v[210:213], v[10:13]
	v_mfma_f32_16x16x32_bf16 v[62:65], v[134:137], v[180:183], v[62:65]
	v_mfma_f32_16x16x32_bf16 v[58:61], v[142:145], v[180:183], v[58:61]
	v_mfma_f32_16x16x32_bf16 v[50:53], v[134:137], v[190:193], v[50:53]
	v_mfma_f32_16x16x32_bf16 v[42:45], v[142:145], v[190:193], v[42:45]
	v_mfma_f32_16x16x32_bf16 v[34:37], v[134:137], v[206:209], v[34:37]
	v_mfma_f32_16x16x32_bf16 v[26:29], v[142:145], v[206:209], v[26:29]
	v_mfma_f32_16x16x32_bf16 v[18:21], v[134:137], v[214:217], v[18:21]
	v_mfma_f32_16x16x32_bf16 v[10:13], v[142:145], v[214:217], v[10:13]
	v_mfma_f32_16x16x32_bf16 v[54:57], v[146:149], v[176:179], v[54:57]
	v_mfma_f32_16x16x32_bf16 v[46:49], v[168:171], v[176:179], v[46:49]
	v_mfma_f32_16x16x32_bf16 v[38:41], v[146:149], v[184:187], v[38:41]
	v_mfma_f32_16x16x32_bf16 v[30:33], v[168:171], v[184:187], v[30:33]
	v_mfma_f32_16x16x32_bf16 v[22:25], v[146:149], v[202:205], v[22:25]
	v_mfma_f32_16x16x32_bf16 v[14:17], v[168:171], v[202:205], v[14:17]
	v_mfma_f32_16x16x32_bf16 v[6:9], v[146:149], v[210:213], v[6:9]
	v_mfma_f32_16x16x32_bf16 v[2:5], v[168:171], v[210:213], v[2:5]
	v_mfma_f32_16x16x32_bf16 v[54:57], v[164:167], v[180:183], v[54:57]
	v_mfma_f32_16x16x32_bf16 v[46:49], v[172:175], v[180:183], v[46:49]
	v_mfma_f32_16x16x32_bf16 v[38:41], v[164:167], v[190:193], v[38:41]
	v_mfma_f32_16x16x32_bf16 v[30:33], v[172:175], v[190:193], v[30:33]
	v_mfma_f32_16x16x32_bf16 v[22:25], v[164:167], v[206:209], v[22:25]
	v_mfma_f32_16x16x32_bf16 v[14:17], v[172:175], v[206:209], v[14:17]
	v_mfma_f32_16x16x32_bf16 v[6:9], v[164:167], v[214:217], v[6:9]
	v_mfma_f32_16x16x32_bf16 v[2:5], v[172:175], v[214:217], v[2:5]
	s_barrier
	s_setprio 0
	s_add_u32 s70, s70, 0x100
	s_addc_u32 s71, s71, 0
	s_cmp_ge_i32 s72, s69
	s_mov_b64 s[48:49], s[8:9]
	s_mov_b32 s50, s72
	s_cbranch_scc0 .LBB0_987
	s_and_b64 vcc, exec, s[38:39]
	s_cbranch_vccz .LBB0_990
	s_barrier

.Ldefbar_skip_2:
.LBB0_1135:
	s_add_i32 s71, s8, 2
	s_add_u32 s0, s58, 0xfff80080
	s_addc_u32 s1, s59, -1
	s_add_i32 s72, 0, 0x10000
	s_cmp_eq_u32 s68, s8
	s_cselect_b32 s63, s43, s1
	s_cselect_b32 s62, s47, s0
	v_add_u32_e32 v146, s72, v149
	s_cselect_b32 s9, s45, s70
	s_cselect_b32 s8, s67, s69
	s_add_i32 s0, 0, 0x14000
	ds_read_b128 v[142:145], v146
	ds_read_b128 v[152:155], v146 offset:1024
	ds_read_b128 v[156:159], v146 offset:2048
	ds_read_b128 v[160:163], v146 offset:3072
	v_add_u32_e32 v146, s0, v149
	ds_read_b128 v[164:167], v146
	ds_read_b128 v[168:171], v146 offset:1024
	ds_read_b128 v[172:175], v146 offset:2048
	ds_read_b128 v[176:179], v146 offset:3072
	s_add_i32 m0, s27, 0xc000
	ds_read_b128 v[180:183], v151
	ds_read_b128 v[184:187], v151 offset:1024
	ds_read_b128 v[188:191], v151 offset:2048
	ds_read_b128 v[192:195], v151 offset:3072
	ds_read_b128 v[202:205], v151 offset:4096
	ds_read_b128 v[206:209], v151 offset:5120
	ds_read_b128 v[210:213], v151 offset:6144
	ds_read_b128 v[214:217], v151 offset:7168
	global_load_lds_dwordx4 v140, s[58:59]
	s_add_i32 m0, s27, 0xe000
	s_nop 0
	global_load_lds_dwordx4 v138, s[58:59]
	s_waitcnt vmcnt(8)
	s_waitcnt lgkmcnt(0)
	s_setprio 1
	s_barrier
	v_mfma_f32_16x16x32_bf16 v[126:129], v[142:145], v[180:183], v[126:129]
	v_mfma_f32_16x16x32_bf16 v[122:125], v[156:159], v[180:183], v[122:125]
	v_mfma_f32_16x16x32_bf16 v[118:121], v[142:145], v[188:191], v[118:121]
	v_mfma_f32_16x16x32_bf16 v[110:113], v[156:159], v[188:191], v[110:113]
	v_mfma_f32_16x16x32_bf16 v[102:105], v[142:145], v[202:205], v[102:105]
	v_mfma_f32_16x16x32_bf16 v[94:97], v[156:159], v[202:205], v[94:97]
	v_mfma_f32_16x16x32_bf16 v[86:89], v[142:145], v[210:213], v[86:89]
	v_mfma_f32_16x16x32_bf16 v[78:81], v[156:159], v[210:213], v[78:81]
	v_mfma_f32_16x16x32_bf16 v[126:129], v[152:155], v[184:187], v[126:129]
	v_mfma_f32_16x16x32_bf16 v[122:125], v[160:163], v[184:187], v[122:125]
	v_mfma_f32_16x16x32_bf16 v[118:121], v[152:155], v[192:195], v[118:121]
	v_mfma_f32_16x16x32_bf16 v[110:113], v[160:163], v[192:195], v[110:113]
	v_mfma_f32_16x16x32_bf16 v[102:105], v[152:155], v[206:209], v[102:105]
	v_mfma_f32_16x16x32_bf16 v[94:97], v[160:163], v[206:209], v[94:97]
	v_mfma_f32_16x16x32_bf16 v[86:89], v[152:155], v[214:217], v[86:89]
	v_mfma_f32_16x16x32_bf16 v[78:81], v[160:163], v[214:217], v[78:81]
	v_mfma_f32_16x16x32_bf16 v[114:117], v[164:167], v[180:183], v[114:117]
	v_mfma_f32_16x16x32_bf16 v[106:109], v[172:175], v[180:183], v[106:109]
	v_mfma_f32_16x16x32_bf16 v[98:101], v[164:167], v[188:191], v[98:101]
	v_mfma_f32_16x16x32_bf16 v[90:93], v[172:175], v[188:191], v[90:93]
	v_mfma_f32_16x16x32_bf16 v[82:85], v[164:167], v[202:205], v[82:85]
	v_mfma_f32_16x16x32_bf16 v[74:77], v[172:175], v[202:205], v[74:77]
	v_mfma_f32_16x16x32_bf16 v[70:73], v[164:167], v[210:213], v[70:73]
	v_mfma_f32_16x16x32_bf16 v[66:69], v[172:175], v[210:213], v[66:69]
	v_mfma_f32_16x16x32_bf16 v[114:117], v[168:171], v[184:187], v[114:117]
	v_mfma_f32_16x16x32_bf16 v[106:109], v[176:179], v[184:187], v[106:109]
	v_mfma_f32_16x16x32_bf16 v[98:101], v[168:171], v[192:195], v[98:101]
	v_mfma_f32_16x16x32_bf16 v[90:93], v[176:179], v[192:195], v[90:93]
	v_mfma_f32_16x16x32_bf16 v[82:85], v[168:171], v[206:209], v[82:85]
	v_mfma_f32_16x16x32_bf16 v[74:77], v[176:179], v[206:209], v[74:77]
	v_mfma_f32_16x16x32_bf16 v[70:73], v[168:171], v[214:217], v[70:73]
	v_mfma_f32_16x16x32_bf16 v[66:69], v[176:179], v[214:217], v[66:69]
	s_barrier
	s_setprio 0
	s_add_i32 s1, s72, s26
	s_add_u32 s98, s8, s16
	s_addc_u32 s99, s9, s17
	s_mov_b32 m0, s1
	ds_read_b128 v[180:183], v151 offset:16384
	ds_read_b128 v[184:187], v151 offset:17408
	ds_read_b128 v[188:191], v151 offset:18432
	ds_read_b128 v[192:195], v151 offset:19456
	ds_read_b128 v[202:205], v151 offset:20480
	ds_read_b128 v[206:209], v151 offset:21504
	ds_read_b128 v[210:213], v151 offset:22528
	ds_read_b128 v[214:217], v151 offset:23552
	global_load_lds_dwordx4 v196, s[8:9]
	s_add_i32 m0, s1, 0x2000
	s_add_u32 s72, s8, 0x80000
	s_addc_u32 s73, s9, 0
	s_add_i32 s0, s0, s26
	global_load_lds_dwordx4 v130, s[8:9]
	s_mov_b32 m0, s0
	s_nop 0
	global_load_lds_dwordx4 v196, s[72:73]
	s_add_i32 m0, s0, 0x2000
	s_nop 0
	global_load_lds_dwordx4 v130, s[72:73]
	s_add_u32 s78, s62, s16
	s_addc_u32 s79, s63, s17
	s_mov_b32 m0, s27
	s_nop 0
	global_load_lds_dwordx4 v134, s[62:63]
	s_mov_b32 m0, s28
	s_nop 0
	global_load_lds_dwordx4 v132, s[62:63]
	s_waitcnt vmcnt(8)
	s_waitcnt lgkmcnt(0)
	s_setprio 1
	s_barrier
	v_mfma_f32_16x16x32_bf16 v[62:65], v[142:145], v[180:183], v[62:65]
	v_mfma_f32_16x16x32_bf16 v[58:61], v[156:159], v[180:183], v[58:61]
	v_mfma_f32_16x16x32_bf16 v[54:57], v[142:145], v[188:191], v[54:57]
	v_mfma_f32_16x16x32_bf16 v[46:49], v[156:159], v[188:191], v[46:49]
	v_mfma_f32_16x16x32_bf16 v[38:41], v[142:145], v[202:205], v[38:41]
	v_mfma_f32_16x16x32_bf16 v[30:33], v[156:159], v[202:205], v[30:33]
	v_mfma_f32_16x16x32_bf16 v[22:25], v[142:145], v[210:213], v[22:25]
	v_mfma_f32_16x16x32_bf16 v[14:17], v[156:159], v[210:213], v[14:17]
	v_mfma_f32_16x16x32_bf16 v[62:65], v[152:155], v[184:187], v[62:65]
	v_mfma_f32_16x16x32_bf16 v[58:61], v[160:163], v[184:187], v[58:61]
	v_mfma_f32_16x16x32_bf16 v[54:57], v[152:155], v[192:195], v[54:57]
	v_mfma_f32_16x16x32_bf16 v[46:49], v[160:163], v[192:195], v[46:49]
	v_mfma_f32_16x16x32_bf16 v[38:41], v[152:155], v[206:209], v[38:41]
	v_mfma_f32_16x16x32_bf16 v[30:33], v[160:163], v[206:209], v[30:33]
	v_mfma_f32_16x16x32_bf16 v[22:25], v[152:155], v[214:217], v[22:25]
	v_mfma_f32_16x16x32_bf16 v[14:17], v[160:163], v[214:217], v[14:17]
	v_mfma_f32_16x16x32_bf16 v[50:53], v[164:167], v[180:183], v[50:53]
	v_mfma_f32_16x16x32_bf16 v[42:45], v[172:175], v[180:183], v[42:45]
	v_mfma_f32_16x16x32_bf16 v[34:37], v[164:167], v[188:191], v[34:37]
	v_mfma_f32_16x16x32_bf16 v[26:29], v[172:175], v[188:191], v[26:29]
	v_mfma_f32_16x16x32_bf16 v[18:21], v[164:167], v[202:205], v[18:21]
	v_mfma_f32_16x16x32_bf16 v[10:13], v[172:175], v[202:205], v[10:13]
	v_mfma_f32_16x16x32_bf16 v[6:9], v[164:167], v[210:213], v[6:9]
	v_mfma_f32_16x16x32_bf16 v[2:5], v[172:175], v[210:213], v[2:5]
	v_mfma_f32_16x16x32_bf16 v[50:53], v[168:171], v[184:187], v[50:53]
	v_mfma_f32_16x16x32_bf16 v[42:45], v[176:179], v[184:187], v[42:45]
	v_mfma_f32_16x16x32_bf16 v[34:37], v[168:171], v[192:195], v[34:37]
	v_mfma_f32_16x16x32_bf16 v[26:29], v[176:179], v[192:195], v[26:29]
	v_mfma_f32_16x16x32_bf16 v[18:21], v[168:171], v[206:209], v[18:21]
	v_mfma_f32_16x16x32_bf16 v[10:13], v[176:179], v[206:209], v[10:13]
	v_mfma_f32_16x16x32_bf16 v[6:9], v[168:171], v[214:217], v[6:9]
	v_mfma_f32_16x16x32_bf16 v[2:5], v[176:179], v[214:217], v[2:5]
	s_barrier
	s_setprio 0
	s_add_i32 s0, 0, 0x18000
	s_add_i32 s1, 0, 0x1c000
	v_add_u32_e32 v160, s0, v149
	v_add_u32_e32 v176, s1, v149
	ds_read_b128 v[142:145], v160
	ds_read_b128 v[152:155], v160 offset:1024
	ds_read_b128 v[156:159], v160 offset:2048
	ds_read_b128 v[160:163], v160 offset:3072
	ds_read_b128 v[164:167], v176
	ds_read_b128 v[168:171], v176 offset:1024
	ds_read_b128 v[172:175], v176 offset:2048
	ds_read_b128 v[176:179], v176 offset:3072
	s_add_u32 s62, s62, 0x80000
	s_addc_u32 s63, s63, 0
	s_mov_b32 m0, s29
	ds_read_b128 v[180:183], v151 offset:32768
	ds_read_b128 v[184:187], v151 offset:33792
	ds_read_b128 v[188:191], v151 offset:34816
	ds_read_b128 v[192:195], v151 offset:35840
	ds_read_b128 v[202:205], v151 offset:36864
	ds_read_b128 v[206:209], v151 offset:37888
	ds_read_b128 v[210:213], v151 offset:38912
	ds_read_b128 v[214:217], v151 offset:39936
	global_load_lds_dwordx4 v134, s[62:63]
	s_mov_b32 m0, s30
	s_nop 0
	global_load_lds_dwordx4 v132, s[62:63]
	s_waitcnt vmcnt(8)
	s_waitcnt lgkmcnt(0)
	s_setprio 1
	s_barrier
	v_mfma_f32_16x16x32_bf16 v[126:129], v[142:145], v[180:183], v[126:129]
	v_mfma_f32_16x16x32_bf16 v[122:125], v[156:159], v[180:183], v[122:125]
	v_mfma_f32_16x16x32_bf16 v[118:121], v[142:145], v[188:191], v[118:121]
	v_mfma_f32_16x16x32_bf16 v[110:113], v[156:159], v[188:191], v[110:113]
	v_mfma_f32_16x16x32_bf16 v[102:105], v[142:145], v[202:205], v[102:105]
	v_mfma_f32_16x16x32_bf16 v[94:97], v[156:159], v[202:205], v[94:97]
	v_mfma_f32_16x16x32_bf16 v[86:89], v[142:145], v[210:213], v[86:89]
	v_mfma_f32_16x16x32_bf16 v[78:81], v[156:159], v[210:213], v[78:81]
	v_mfma_f32_16x16x32_bf16 v[126:129], v[152:155], v[184:187], v[126:129]
	v_mfma_f32_16x16x32_bf16 v[122:125], v[160:163], v[184:187], v[122:125]
	v_mfma_f32_16x16x32_bf16 v[118:121], v[152:155], v[192:195], v[118:121]
	v_mfma_f32_16x16x32_bf16 v[110:113], v[160:163], v[192:195], v[110:113]
	v_mfma_f32_16x16x32_bf16 v[102:105], v[152:155], v[206:209], v[102:105]
	v_mfma_f32_16x16x32_bf16 v[94:97], v[160:163], v[206:209], v[94:97]
	v_mfma_f32_16x16x32_bf16 v[86:89], v[152:155], v[214:217], v[86:89]
	v_mfma_f32_16x16x32_bf16 v[78:81], v[160:163], v[214:217], v[78:81]
	v_mfma_f32_16x16x32_bf16 v[114:117], v[164:167], v[180:183], v[114:117]
	v_mfma_f32_16x16x32_bf16 v[106:109], v[172:175], v[180:183], v[106:109]
	v_mfma_f32_16x16x32_bf16 v[98:101], v[164:167], v[188:191], v[98:101]
	v_mfma_f32_16x16x32_bf16 v[90:93], v[172:175], v[188:191], v[90:93]
	v_mfma_f32_16x16x32_bf16 v[82:85], v[164:167], v[202:205], v[82:85]
	v_mfma_f32_16x16x32_bf16 v[74:77], v[172:175], v[202:205], v[74:77]
	v_mfma_f32_16x16x32_bf16 v[70:73], v[164:167], v[210:213], v[70:73]
	v_mfma_f32_16x16x32_bf16 v[66:69], v[172:175], v[210:213], v[66:69]
	v_mfma_f32_16x16x32_bf16 v[114:117], v[168:171], v[184:187], v[114:117]
	v_mfma_f32_16x16x32_bf16 v[106:109], v[176:179], v[184:187], v[106:109]
	v_mfma_f32_16x16x32_bf16 v[98:101], v[168:171], v[192:195], v[98:101]
	v_mfma_f32_16x16x32_bf16 v[90:93], v[176:179], v[192:195], v[90:93]
	v_mfma_f32_16x16x32_bf16 v[82:85], v[168:171], v[206:209], v[82:85]
	v_mfma_f32_16x16x32_bf16 v[74:77], v[176:179], v[206:209], v[74:77]
	v_mfma_f32_16x16x32_bf16 v[70:73], v[168:171], v[214:217], v[70:73]
	v_mfma_f32_16x16x32_bf16 v[66:69], v[176:179], v[214:217], v[66:69]
	s_barrier
	s_setprio 0
	s_add_i32 s0, s0, s26
	s_mov_b32 m0, s0
	ds_read_b128 v[180:183], v151 offset:49152
	ds_read_b128 v[184:187], v151 offset:50176
	ds_read_b128 v[188:191], v151 offset:51200
	ds_read_b128 v[192:195], v151 offset:52224
	ds_read_b128 v[202:205], v151 offset:53248
	ds_read_b128 v[206:209], v151 offset:54272
	ds_read_b128 v[210:213], v151 offset:55296
	ds_read_b128 v[214:217], v151 offset:56320
	global_load_lds_dwordx4 v196, s[98:99]
	s_add_i32 m0, s0, 0x2000
	s_add_u32 s8, s8, 0x80080
	s_addc_u32 s9, s9, 0
	s_add_i32 s0, s1, s26
	global_load_lds_dwordx4 v130, s[98:99]
	s_mov_b32 m0, s0
	s_nop 0
	global_load_lds_dwordx4 v196, s[8:9]
	s_add_i32 m0, s0, 0x2000
	s_nop 0
	global_load_lds_dwordx4 v130, s[8:9]
	s_mov_b32 m0, s31
	s_nop 0
	global_load_lds_dwordx4 v134, s[78:79]
	s_mov_b32 m0, s34
	s_nop 0
	global_load_lds_dwordx4 v132, s[78:79]
	s_waitcnt vmcnt(8)
	s_waitcnt lgkmcnt(0)
	s_setprio 1
	s_barrier
	v_mfma_f32_16x16x32_bf16 v[62:65], v[142:145], v[180:183], v[62:65]
	v_mfma_f32_16x16x32_bf16 v[58:61], v[156:159], v[180:183], v[58:61]
	v_mfma_f32_16x16x32_bf16 v[54:57], v[142:145], v[188:191], v[54:57]
	v_mfma_f32_16x16x32_bf16 v[46:49], v[156:159], v[188:191], v[46:49]
	v_mfma_f32_16x16x32_bf16 v[38:41], v[142:145], v[202:205], v[38:41]
	v_mfma_f32_16x16x32_bf16 v[30:33], v[156:159], v[202:205], v[30:33]
	v_mfma_f32_16x16x32_bf16 v[22:25], v[142:145], v[210:213], v[22:25]
	v_mfma_f32_16x16x32_bf16 v[14:17], v[156:159], v[210:213], v[14:17]
	v_mfma_f32_16x16x32_bf16 v[62:65], v[152:155], v[184:187], v[62:65]
	v_mfma_f32_16x16x32_bf16 v[58:61], v[160:163], v[184:187], v[58:61]
	v_mfma_f32_16x16x32_bf16 v[54:57], v[152:155], v[192:195], v[54:57]
	v_mfma_f32_16x16x32_bf16 v[46:49], v[160:163], v[192:195], v[46:49]
	v_mfma_f32_16x16x32_bf16 v[38:41], v[152:155], v[206:209], v[38:41]
	v_mfma_f32_16x16x32_bf16 v[30:33], v[160:163], v[206:209], v[30:33]
	v_mfma_f32_16x16x32_bf16 v[22:25], v[152:155], v[214:217], v[22:25]
	v_mfma_f32_16x16x32_bf16 v[14:17], v[160:163], v[214:217], v[14:17]
	v_mfma_f32_16x16x32_bf16 v[50:53], v[164:167], v[180:183], v[50:53]
	v_mfma_f32_16x16x32_bf16 v[42:45], v[172:175], v[180:183], v[42:45]
	v_mfma_f32_16x16x32_bf16 v[34:37], v[164:167], v[188:191], v[34:37]
	v_mfma_f32_16x16x32_bf16 v[26:29], v[172:175], v[188:191], v[26:29]
	v_mfma_f32_16x16x32_bf16 v[18:21], v[164:167], v[202:205], v[18:21]
	v_mfma_f32_16x16x32_bf16 v[10:13], v[172:175], v[202:205], v[10:13]
	v_mfma_f32_16x16x32_bf16 v[6:9], v[164:167], v[210:213], v[6:9]
	v_mfma_f32_16x16x32_bf16 v[2:5], v[172:175], v[210:213], v[2:5]
	v_mfma_f32_16x16x32_bf16 v[50:53], v[168:171], v[184:187], v[50:53]
	v_mfma_f32_16x16x32_bf16 v[42:45], v[176:179], v[184:187], v[42:45]
	v_mfma_f32_16x16x32_bf16 v[34:37], v[168:171], v[192:195], v[34:37]
	v_mfma_f32_16x16x32_bf16 v[26:29], v[176:179], v[192:195], v[26:29]
	v_mfma_f32_16x16x32_bf16 v[18:21], v[168:171], v[206:209], v[18:21]
	v_mfma_f32_16x16x32_bf16 v[10:13], v[176:179], v[206:209], v[10:13]
	v_mfma_f32_16x16x32_bf16 v[6:9], v[168:171], v[214:217], v[6:9]
	v_mfma_f32_16x16x32_bf16 v[2:5], v[176:179], v[214:217], v[2:5]
	s_barrier
	s_setprio 0
	s_add_u32 s69, s69, 0x100
	s_addc_u32 s70, s70, 0
	s_add_u32 s58, s58, 0x100
	s_addc_u32 s59, s59, 0
	s_cmp_ge_i32 s71, s64
	s_mov_b32 s8, s71
	s_cbranch_scc0 .LBB0_1135
	s_and_b64 vcc, exec, s[38:39]
	s_cbranch_vccz .LBB0_1138
	s_barrier

.Ldefbar_skip_3:
.LBB0_2239:
	s_add_i32 s73, s8, 2
	s_add_u32 s0, s44, 0xfff00080
	s_addc_u32 s1, s45, -1
	s_add_i32 s77, 0, 0x10000
	s_cmp_eq_u32 s70, s8
	s_cselect_b32 s67, s51, s1
	s_cselect_b32 s66, s53, s0
	s_cselect_b32 s9, s49, s72
	s_cselect_b32 s8, s69, s71
	s_add_i32 s78, 0, 0x14000
	v_add_u32_e32 v142, s77, v244
	v_add_u32_e32 v158, s78, v244
	ds_read_b128 v[130:133], v142
	ds_read_b128 v[134:137], v142 offset:1024
	ds_read_b128 v[138:141], v142 offset:2048
	ds_read_b128 v[142:145], v142 offset:3072
	ds_read_b128 v[146:149], v158
	ds_read_b128 v[150:153], v158 offset:1024
	ds_read_b128 v[154:157], v158 offset:2048
	ds_read_b128 v[158:161], v158 offset:3072
	s_add_i32 m0, s3, 0xc000
	ds_read_b128 v[162:165], v246
	ds_read_b128 v[166:169], v246 offset:1024
	ds_read_b128 v[170:173], v246 offset:2048
	ds_read_b128 v[174:177], v246 offset:3072
	ds_read_b128 v[178:181], v246 offset:4096
	ds_read_b128 v[182:185], v246 offset:5120
	ds_read_b128 v[186:189], v246 offset:6144
	ds_read_b128 v[190:193], v246 offset:7168
	global_load_lds_dwordx4 v210, s[44:45]
	s_add_i32 m0, s3, 0xe000
	s_nop 0
	global_load_lds_dwordx4 v208, s[44:45]
	s_waitcnt vmcnt(8)
	s_waitcnt lgkmcnt(0)
	s_setprio 1
	s_barrier
	v_mfma_f32_16x16x32_bf16 v[126:129], v[130:133], v[162:165], v[126:129]
	v_mfma_f32_16x16x32_bf16 v[122:125], v[138:141], v[162:165], v[122:125]
	v_mfma_f32_16x16x32_bf16 v[110:113], v[130:133], v[170:173], v[110:113]
	v_mfma_f32_16x16x32_bf16 v[106:109], v[138:141], v[170:173], v[106:109]
	v_mfma_f32_16x16x32_bf16 v[94:97], v[130:133], v[178:181], v[94:97]
	v_mfma_f32_16x16x32_bf16 v[90:93], v[138:141], v[178:181], v[90:93]
	v_mfma_f32_16x16x32_bf16 v[78:81], v[130:133], v[186:189], v[78:81]
	v_mfma_f32_16x16x32_bf16 v[74:77], v[138:141], v[186:189], v[74:77]
	v_mfma_f32_16x16x32_bf16 v[126:129], v[134:137], v[166:169], v[126:129]
	v_mfma_f32_16x16x32_bf16 v[122:125], v[142:145], v[166:169], v[122:125]
	v_mfma_f32_16x16x32_bf16 v[110:113], v[134:137], v[174:177], v[110:113]
	v_mfma_f32_16x16x32_bf16 v[106:109], v[142:145], v[174:177], v[106:109]
	v_mfma_f32_16x16x32_bf16 v[94:97], v[134:137], v[182:185], v[94:97]
	v_mfma_f32_16x16x32_bf16 v[90:93], v[142:145], v[182:185], v[90:93]
	v_mfma_f32_16x16x32_bf16 v[78:81], v[134:137], v[190:193], v[78:81]
	v_mfma_f32_16x16x32_bf16 v[74:77], v[142:145], v[190:193], v[74:77]
	v_mfma_f32_16x16x32_bf16 v[118:121], v[146:149], v[162:165], v[118:121]
	v_mfma_f32_16x16x32_bf16 v[114:117], v[154:157], v[162:165], v[114:117]
	v_mfma_f32_16x16x32_bf16 v[102:105], v[146:149], v[170:173], v[102:105]
	v_mfma_f32_16x16x32_bf16 v[98:101], v[154:157], v[170:173], v[98:101]
	v_mfma_f32_16x16x32_bf16 v[86:89], v[146:149], v[178:181], v[86:89]
	v_mfma_f32_16x16x32_bf16 v[82:85], v[154:157], v[178:181], v[82:85]
	v_mfma_f32_16x16x32_bf16 v[70:73], v[146:149], v[186:189], v[70:73]
	v_mfma_f32_16x16x32_bf16 v[66:69], v[154:157], v[186:189], v[66:69]
	v_mfma_f32_16x16x32_bf16 v[118:121], v[150:153], v[166:169], v[118:121]
	v_mfma_f32_16x16x32_bf16 v[114:117], v[158:161], v[166:169], v[114:117]
	v_mfma_f32_16x16x32_bf16 v[102:105], v[150:153], v[174:177], v[102:105]
	v_mfma_f32_16x16x32_bf16 v[98:101], v[158:161], v[174:177], v[98:101]
	v_mfma_f32_16x16x32_bf16 v[86:89], v[150:153], v[182:185], v[86:89]
	v_mfma_f32_16x16x32_bf16 v[82:85], v[158:161], v[182:185], v[82:85]
	v_mfma_f32_16x16x32_bf16 v[70:73], v[150:153], v[190:193], v[70:73]
	v_mfma_f32_16x16x32_bf16 v[66:69], v[158:161], v[190:193], v[66:69]
	s_barrier
	s_setprio 0
	s_add_i32 s0, s77, s2
	s_add_u32 s98, s8, s16
	s_addc_u32 s99, s9, s17
	s_mov_b32 m0, s0
	ds_read_b128 v[162:165], v246 offset:16384
	ds_read_b128 v[166:169], v246 offset:17408
	ds_read_b128 v[170:173], v246 offset:18432
	ds_read_b128 v[174:177], v246 offset:19456
	ds_read_b128 v[178:181], v246 offset:20480
	ds_read_b128 v[182:185], v246 offset:21504
	ds_read_b128 v[186:189], v246 offset:22528
	ds_read_b128 v[190:193], v246 offset:23552
	global_load_lds_dwordx4 v196, s[8:9]
	s_add_i32 m0, s0, 0x2000
	s_add_u32 s0, s8, 0x100000
	s_addc_u32 s1, s9, 0
	s_add_i32 s77, s78, s2
	global_load_lds_dwordx4 v202, s[8:9]
	s_mov_b32 m0, s77
	v_lshl_add_u64 v[216:217], s[66:67], 0, v[204:205]
	global_load_lds_dwordx4 v196, s[0:1]
	s_add_i32 m0, s77, 0x2000
	s_nop 0
	global_load_lds_dwordx4 v202, s[0:1]
	v_lshl_add_u64 v[214:215], s[66:67], 0, v[206:207]
	s_mov_b32 m0, s3
	s_nop 0
	global_load_lds_dwordx4 v206, s[66:67]
	s_mov_b32 m0, s10
	s_nop 0
	global_load_lds_dwordx4 v204, s[66:67]
	s_waitcnt vmcnt(8)
	s_waitcnt lgkmcnt(0)
	s_setprio 1
	s_barrier
	v_mfma_f32_16x16x32_bf16 v[62:65], v[130:133], v[162:165], v[62:65]
	v_mfma_f32_16x16x32_bf16 v[58:61], v[138:141], v[162:165], v[58:61]
	v_mfma_f32_16x16x32_bf16 v[46:49], v[130:133], v[170:173], v[46:49]
	v_mfma_f32_16x16x32_bf16 v[42:45], v[138:141], v[170:173], v[42:45]
	v_mfma_f32_16x16x32_bf16 v[30:33], v[130:133], v[178:181], v[30:33]
	v_mfma_f32_16x16x32_bf16 v[26:29], v[138:141], v[178:181], v[26:29]
	v_mfma_f32_16x16x32_bf16 v[14:17], v[130:133], v[186:189], v[14:17]
	v_mfma_f32_16x16x32_bf16 v[10:13], v[138:141], v[186:189], v[10:13]
	v_mfma_f32_16x16x32_bf16 v[62:65], v[134:137], v[166:169], v[62:65]
	v_mfma_f32_16x16x32_bf16 v[58:61], v[142:145], v[166:169], v[58:61]
	v_mfma_f32_16x16x32_bf16 v[46:49], v[134:137], v[174:177], v[46:49]
	v_mfma_f32_16x16x32_bf16 v[42:45], v[142:145], v[174:177], v[42:45]
	v_mfma_f32_16x16x32_bf16 v[30:33], v[134:137], v[182:185], v[30:33]
	v_mfma_f32_16x16x32_bf16 v[26:29], v[142:145], v[182:185], v[26:29]
	v_mfma_f32_16x16x32_bf16 v[14:17], v[134:137], v[190:193], v[14:17]
	v_mfma_f32_16x16x32_bf16 v[10:13], v[142:145], v[190:193], v[10:13]
	v_mfma_f32_16x16x32_bf16 v[54:57], v[146:149], v[162:165], v[54:57]
	v_mfma_f32_16x16x32_bf16 v[50:53], v[154:157], v[162:165], v[50:53]
	v_mfma_f32_16x16x32_bf16 v[38:41], v[146:149], v[170:173], v[38:41]
	v_mfma_f32_16x16x32_bf16 v[34:37], v[154:157], v[170:173], v[34:37]
	v_mfma_f32_16x16x32_bf16 v[22:25], v[146:149], v[178:181], v[22:25]
	v_mfma_f32_16x16x32_bf16 v[18:21], v[154:157], v[178:181], v[18:21]
	v_mfma_f32_16x16x32_bf16 v[6:9], v[146:149], v[186:189], v[6:9]
	v_mfma_f32_16x16x32_bf16 v[2:5], v[154:157], v[186:189], v[2:5]
	v_mfma_f32_16x16x32_bf16 v[54:57], v[150:153], v[166:169], v[54:57]
	v_mfma_f32_16x16x32_bf16 v[50:53], v[158:161], v[166:169], v[50:53]
	v_mfma_f32_16x16x32_bf16 v[38:41], v[150:153], v[174:177], v[38:41]
	v_mfma_f32_16x16x32_bf16 v[34:37], v[158:161], v[174:177], v[34:37]
	v_mfma_f32_16x16x32_bf16 v[22:25], v[150:153], v[182:185], v[22:25]
	v_mfma_f32_16x16x32_bf16 v[18:21], v[158:161], v[182:185], v[18:21]
	v_mfma_f32_16x16x32_bf16 v[6:9], v[150:153], v[190:193], v[6:9]
	v_mfma_f32_16x16x32_bf16 v[2:5], v[158:161], v[190:193], v[2:5]
	s_barrier
	s_setprio 0
	s_add_i32 s77, 0, 0x18000
	s_add_i32 s78, 0, 0x1c000
	v_add_u32_e32 v142, s77, v244
	v_add_u32_e32 v158, s78, v244
	ds_read_b128 v[130:133], v142
	ds_read_b128 v[134:137], v142 offset:1024
	ds_read_b128 v[138:141], v142 offset:2048
	ds_read_b128 v[142:145], v142 offset:3072
	ds_read_b128 v[146:149], v158
	ds_read_b128 v[150:153], v158 offset:1024
	ds_read_b128 v[154:157], v158 offset:2048
	ds_read_b128 v[158:161], v158 offset:3072
	s_add_u32 s0, s66, 0x100000
	s_addc_u32 s1, s67, 0
	s_mov_b32 m0, s11
	ds_read_b128 v[162:165], v246 offset:32768
	ds_read_b128 v[166:169], v246 offset:33792
	ds_read_b128 v[170:173], v246 offset:34816
	ds_read_b128 v[174:177], v246 offset:35840
	ds_read_b128 v[178:181], v246 offset:36864
	ds_read_b128 v[182:185], v246 offset:37888
	ds_read_b128 v[186:189], v246 offset:38912
	ds_read_b128 v[190:193], v246 offset:39936
	global_load_lds_dwordx4 v206, s[0:1]
	s_mov_b32 m0, s26
	s_nop 0
	global_load_lds_dwordx4 v204, s[0:1]
	s_waitcnt vmcnt(8)
	s_waitcnt lgkmcnt(0)
	s_setprio 1
	s_barrier
	v_mfma_f32_16x16x32_bf16 v[126:129], v[130:133], v[162:165], v[126:129]
	v_mfma_f32_16x16x32_bf16 v[122:125], v[138:141], v[162:165], v[122:125]
	v_mfma_f32_16x16x32_bf16 v[110:113], v[130:133], v[170:173], v[110:113]
	v_mfma_f32_16x16x32_bf16 v[106:109], v[138:141], v[170:173], v[106:109]
	v_mfma_f32_16x16x32_bf16 v[94:97], v[130:133], v[178:181], v[94:97]
	v_mfma_f32_16x16x32_bf16 v[90:93], v[138:141], v[178:181], v[90:93]
	v_mfma_f32_16x16x32_bf16 v[78:81], v[130:133], v[186:189], v[78:81]
	v_mfma_f32_16x16x32_bf16 v[74:77], v[138:141], v[186:189], v[74:77]
	v_mfma_f32_16x16x32_bf16 v[126:129], v[134:137], v[166:169], v[126:129]
	v_mfma_f32_16x16x32_bf16 v[122:125], v[142:145], v[166:169], v[122:125]
	v_mfma_f32_16x16x32_bf16 v[110:113], v[134:137], v[174:177], v[110:113]
	v_mfma_f32_16x16x32_bf16 v[106:109], v[142:145], v[174:177], v[106:109]
	v_mfma_f32_16x16x32_bf16 v[94:97], v[134:137], v[182:185], v[94:97]
	v_mfma_f32_16x16x32_bf16 v[90:93], v[142:145], v[182:185], v[90:93]
	v_mfma_f32_16x16x32_bf16 v[78:81], v[134:137], v[190:193], v[78:81]
	v_mfma_f32_16x16x32_bf16 v[74:77], v[142:145], v[190:193], v[74:77]
	v_mfma_f32_16x16x32_bf16 v[118:121], v[146:149], v[162:165], v[118:121]
	v_mfma_f32_16x16x32_bf16 v[114:117], v[154:157], v[162:165], v[114:117]
	v_mfma_f32_16x16x32_bf16 v[102:105], v[146:149], v[170:173], v[102:105]
	v_mfma_f32_16x16x32_bf16 v[98:101], v[154:157], v[170:173], v[98:101]
	v_mfma_f32_16x16x32_bf16 v[86:89], v[146:149], v[178:181], v[86:89]
	v_mfma_f32_16x16x32_bf16 v[82:85], v[154:157], v[178:181], v[82:85]
	v_mfma_f32_16x16x32_bf16 v[70:73], v[146:149], v[186:189], v[70:73]
	v_mfma_f32_16x16x32_bf16 v[66:69], v[154:157], v[186:189], v[66:69]
	v_mfma_f32_16x16x32_bf16 v[118:121], v[150:153], v[166:169], v[118:121]
	v_mfma_f32_16x16x32_bf16 v[114:117], v[158:161], v[166:169], v[114:117]
	v_mfma_f32_16x16x32_bf16 v[102:105], v[150:153], v[174:177], v[102:105]
	v_mfma_f32_16x16x32_bf16 v[98:101], v[158:161], v[174:177], v[98:101]
	v_mfma_f32_16x16x32_bf16 v[86:89], v[150:153], v[182:185], v[86:89]
	v_mfma_f32_16x16x32_bf16 v[82:85], v[158:161], v[182:185], v[82:85]
	v_mfma_f32_16x16x32_bf16 v[70:73], v[150:153], v[190:193], v[70:73]
	v_mfma_f32_16x16x32_bf16 v[66:69], v[158:161], v[190:193], v[66:69]
	s_barrier
	s_setprio 0
	s_add_i32 s0, s77, s2
	s_mov_b32 m0, s0
	ds_read_b128 v[162:165], v246 offset:49152
	ds_read_b128 v[166:169], v246 offset:50176
	ds_read_b128 v[170:173], v246 offset:51200
	ds_read_b128 v[174:177], v246 offset:52224
	ds_read_b128 v[178:181], v246 offset:53248
	ds_read_b128 v[182:185], v246 offset:54272
	ds_read_b128 v[186:189], v246 offset:55296
	ds_read_b128 v[190:193], v246 offset:56320
	global_load_lds_dwordx4 v196, s[98:99]
	s_add_i32 m0, s0, 0x2000
	s_add_u32 s0, s8, 0x100080
	s_addc_u32 s1, s9, 0
	s_add_i32 s8, s78, s2
	global_load_lds_dwordx4 v202, s[98:99]
	s_mov_b32 m0, s8
	s_nop 0
	global_load_lds_dwordx4 v196, s[0:1]
	s_add_i32 m0, s8, 0x2000
	s_nop 0
	global_load_lds_dwordx4 v202, s[0:1]
	v_lshl_add_u64 v[194:195], v[214:215], 0, s[16:17]
	s_mov_b32 m0, s27
	s_nop 0
	global_load_lds_dwordx4 v[194:195], off
	v_lshl_add_u64 v[194:195], v[216:217], 0, s[16:17]
	s_mov_b32 m0, s28
	s_nop 0
	global_load_lds_dwordx4 v[194:195], off
	s_waitcnt vmcnt(8)
	s_waitcnt lgkmcnt(0)
	s_setprio 1
	s_barrier
	v_mfma_f32_16x16x32_bf16 v[62:65], v[130:133], v[162:165], v[62:65]
	v_mfma_f32_16x16x32_bf16 v[58:61], v[138:141], v[162:165], v[58:61]
	v_mfma_f32_16x16x32_bf16 v[46:49], v[130:133], v[170:173], v[46:49]
	v_mfma_f32_16x16x32_bf16 v[42:45], v[138:141], v[170:173], v[42:45]
	v_mfma_f32_16x16x32_bf16 v[30:33], v[130:133], v[178:181], v[30:33]
	v_mfma_f32_16x16x32_bf16 v[26:29], v[138:141], v[178:181], v[26:29]
	v_mfma_f32_16x16x32_bf16 v[14:17], v[130:133], v[186:189], v[14:17]
	v_mfma_f32_16x16x32_bf16 v[10:13], v[138:141], v[186:189], v[10:13]
	v_mfma_f32_16x16x32_bf16 v[62:65], v[134:137], v[166:169], v[62:65]
	v_mfma_f32_16x16x32_bf16 v[58:61], v[142:145], v[166:169], v[58:61]
	v_mfma_f32_16x16x32_bf16 v[46:49], v[134:137], v[174:177], v[46:49]
	v_mfma_f32_16x16x32_bf16 v[42:45], v[142:145], v[174:177], v[42:45]
	v_mfma_f32_16x16x32_bf16 v[30:33], v[134:137], v[182:185], v[30:33]
	v_mfma_f32_16x16x32_bf16 v[26:29], v[142:145], v[182:185], v[26:29]
	v_mfma_f32_16x16x32_bf16 v[14:17], v[134:137], v[190:193], v[14:17]
	v_mfma_f32_16x16x32_bf16 v[10:13], v[142:145], v[190:193], v[10:13]
	v_mfma_f32_16x16x32_bf16 v[54:57], v[146:149], v[162:165], v[54:57]
	v_mfma_f32_16x16x32_bf16 v[50:53], v[154:157], v[162:165], v[50:53]
	v_mfma_f32_16x16x32_bf16 v[38:41], v[146:149], v[170:173], v[38:41]
	v_mfma_f32_16x16x32_bf16 v[34:37], v[154:157], v[170:173], v[34:37]
	v_mfma_f32_16x16x32_bf16 v[22:25], v[146:149], v[178:181], v[22:25]
	v_mfma_f32_16x16x32_bf16 v[18:21], v[154:157], v[178:181], v[18:21]
	v_mfma_f32_16x16x32_bf16 v[6:9], v[146:149], v[186:189], v[6:9]
	v_mfma_f32_16x16x32_bf16 v[2:5], v[154:157], v[186:189], v[2:5]
	v_mfma_f32_16x16x32_bf16 v[54:57], v[150:153], v[166:169], v[54:57]
	v_mfma_f32_16x16x32_bf16 v[50:53], v[158:161], v[166:169], v[50:53]
	v_mfma_f32_16x16x32_bf16 v[38:41], v[150:153], v[174:177], v[38:41]
	v_mfma_f32_16x16x32_bf16 v[34:37], v[158:161], v[174:177], v[34:37]
	v_mfma_f32_16x16x32_bf16 v[22:25], v[150:153], v[182:185], v[22:25]
	v_mfma_f32_16x16x32_bf16 v[18:21], v[158:161], v[182:185], v[18:21]
	v_mfma_f32_16x16x32_bf16 v[6:9], v[150:153], v[190:193], v[6:9]
	v_mfma_f32_16x16x32_bf16 v[2:5], v[158:161], v[190:193], v[2:5]
	s_barrier
	s_setprio 0
	s_add_u32 s71, s71, 0x100
	s_addc_u32 s72, s72, 0
	s_add_u32 s44, s44, 0x100
	s_addc_u32 s45, s45, 0
	s_cmp_ge_i32 s73, s35
	s_mov_b32 s8, s73
	s_cbranch_scc0 .LBB0_2239
	s_and_b64 vcc, exec, s[46:47]
	s_cbranch_vccz .LBB0_2242
	s_barrier

.Ldefbar_skip_4:
.LBB0_2357:
	s_add_i32 s77, s8, 2
	s_add_u32 s0, s62, 0xfff80080
	s_addc_u32 s1, s63, -1
	s_add_i32 s78, 0, 0x10000
	s_cmp_eq_u32 s71, s8
	s_cselect_b32 s65, s41, s1
	s_cselect_b32 s64, s45, s0
	s_cselect_b32 s9, s43, s73
	s_cselect_b32 s8, s70, s72
	s_add_i32 s79, 0, 0x14000
	v_add_u32_e32 v142, s78, v188
	v_add_u32_e32 v158, s79, v188
	ds_read_b128 v[130:133], v142
	ds_read_b128 v[134:137], v142 offset:1024
	ds_read_b128 v[138:141], v142 offset:2048
	ds_read_b128 v[142:145], v142 offset:3072
	ds_read_b128 v[146:149], v158
	ds_read_b128 v[150:153], v158 offset:1024
	ds_read_b128 v[154:157], v158 offset:2048
	ds_read_b128 v[158:161], v158 offset:3072
	s_add_i32 m0, s27, 0xc000
	ds_read_b128 v[162:165], v189
	ds_read_b128 v[180:183], v189 offset:1024
	ds_read_b128 v[184:187], v189 offset:2048
	ds_read_b128 v[190:193], v189 offset:3072
	ds_read_b128 v[202:205], v189 offset:4096
	ds_read_b128 v[206:209], v189 offset:5120
	ds_read_b128 v[210:213], v189 offset:6144
	ds_read_b128 v[214:217], v189 offset:7168
	global_load_lds_dwordx4 v178, s[62:63]
	s_add_i32 m0, s27, 0xe000
	s_nop 0
	global_load_lds_dwordx4 v176, s[62:63]
	s_waitcnt vmcnt(8)
	s_waitcnt lgkmcnt(0)
	s_setprio 1
	s_barrier
	v_mfma_f32_16x16x32_bf16 v[126:129], v[130:133], v[162:165], v[126:129]
	v_mfma_f32_16x16x32_bf16 v[122:125], v[138:141], v[162:165], v[122:125]
	v_mfma_f32_16x16x32_bf16 v[110:113], v[130:133], v[184:187], v[110:113]
	v_mfma_f32_16x16x32_bf16 v[106:109], v[138:141], v[184:187], v[106:109]
	v_mfma_f32_16x16x32_bf16 v[98:101], v[130:133], v[202:205], v[98:101]
	v_mfma_f32_16x16x32_bf16 v[90:93], v[138:141], v[202:205], v[90:93]
	v_mfma_f32_16x16x32_bf16 v[82:85], v[130:133], v[210:213], v[82:85]
	v_mfma_f32_16x16x32_bf16 v[74:77], v[138:141], v[210:213], v[74:77]
	v_mfma_f32_16x16x32_bf16 v[126:129], v[134:137], v[180:183], v[126:129]
	v_mfma_f32_16x16x32_bf16 v[122:125], v[142:145], v[180:183], v[122:125]
	v_mfma_f32_16x16x32_bf16 v[110:113], v[134:137], v[190:193], v[110:113]
	v_mfma_f32_16x16x32_bf16 v[106:109], v[142:145], v[190:193], v[106:109]
	v_mfma_f32_16x16x32_bf16 v[98:101], v[134:137], v[206:209], v[98:101]
	v_mfma_f32_16x16x32_bf16 v[90:93], v[142:145], v[206:209], v[90:93]
	v_mfma_f32_16x16x32_bf16 v[82:85], v[134:137], v[214:217], v[82:85]
	v_mfma_f32_16x16x32_bf16 v[74:77], v[142:145], v[214:217], v[74:77]
	v_mfma_f32_16x16x32_bf16 v[118:121], v[146:149], v[162:165], v[118:121]
	v_mfma_f32_16x16x32_bf16 v[114:117], v[154:157], v[162:165], v[114:117]
	v_mfma_f32_16x16x32_bf16 v[102:105], v[146:149], v[184:187], v[102:105]
	v_mfma_f32_16x16x32_bf16 v[94:97], v[154:157], v[184:187], v[94:97]
	v_mfma_f32_16x16x32_bf16 v[86:89], v[146:149], v[202:205], v[86:89]
	v_mfma_f32_16x16x32_bf16 v[78:81], v[154:157], v[202:205], v[78:81]
	v_mfma_f32_16x16x32_bf16 v[70:73], v[146:149], v[210:213], v[70:73]
	v_mfma_f32_16x16x32_bf16 v[66:69], v[154:157], v[210:213], v[66:69]
	v_mfma_f32_16x16x32_bf16 v[118:121], v[150:153], v[180:183], v[118:121]
	v_mfma_f32_16x16x32_bf16 v[114:117], v[158:161], v[180:183], v[114:117]
	v_mfma_f32_16x16x32_bf16 v[102:105], v[150:153], v[190:193], v[102:105]
	v_mfma_f32_16x16x32_bf16 v[94:97], v[158:161], v[190:193], v[94:97]
	v_mfma_f32_16x16x32_bf16 v[86:89], v[150:153], v[206:209], v[86:89]
	v_mfma_f32_16x16x32_bf16 v[78:81], v[158:161], v[206:209], v[78:81]
	v_mfma_f32_16x16x32_bf16 v[70:73], v[150:153], v[214:217], v[70:73]
	v_mfma_f32_16x16x32_bf16 v[66:69], v[158:161], v[214:217], v[66:69]
	s_barrier
	s_setprio 0
	s_add_i32 s0, s78, s26
	s_add_u32 s98, s8, s16
	s_addc_u32 s99, s9, s17
	s_mov_b32 m0, s0
	ds_read_b128 v[162:165], v189 offset:16384
	ds_read_b128 v[180:183], v189 offset:17408
	ds_read_b128 v[184:187], v189 offset:18432
	ds_read_b128 v[190:193], v189 offset:19456
	ds_read_b128 v[202:205], v189 offset:20480
	ds_read_b128 v[206:209], v189 offset:21504
	ds_read_b128 v[210:213], v189 offset:22528
	ds_read_b128 v[214:217], v189 offset:23552
	global_load_lds_dwordx4 v196, s[8:9]
	s_add_i32 m0, s0, 0x2000
	s_add_u32 s0, s8, 0x80000
	s_addc_u32 s1, s9, 0
	s_add_i32 s78, s79, s26
	global_load_lds_dwordx4 v170, s[8:9]
	s_mov_b32 m0, s78
	v_lshl_add_u64 v[222:223], s[64:65], 0, v[168:169]
	global_load_lds_dwordx4 v196, s[0:1]
	s_add_i32 m0, s78, 0x2000
	s_nop 0
	global_load_lds_dwordx4 v170, s[0:1]
	v_lshl_add_u64 v[220:221], s[64:65], 0, v[166:167]
	s_mov_b32 m0, s27
	s_nop 0
	global_load_lds_dwordx4 v166, s[64:65]
	s_mov_b32 m0, s28
	s_nop 0
	global_load_lds_dwordx4 v168, s[64:65]
	s_waitcnt vmcnt(8)
	s_waitcnt lgkmcnt(0)
	s_setprio 1
	s_barrier
	v_mfma_f32_16x16x32_bf16 v[62:65], v[130:133], v[162:165], v[62:65]
	v_mfma_f32_16x16x32_bf16 v[58:61], v[138:141], v[162:165], v[58:61]
	v_mfma_f32_16x16x32_bf16 v[50:53], v[130:133], v[184:187], v[50:53]
	v_mfma_f32_16x16x32_bf16 v[42:45], v[138:141], v[184:187], v[42:45]
	v_mfma_f32_16x16x32_bf16 v[34:37], v[130:133], v[202:205], v[34:37]
	v_mfma_f32_16x16x32_bf16 v[26:29], v[138:141], v[202:205], v[26:29]
	v_mfma_f32_16x16x32_bf16 v[18:21], v[130:133], v[210:213], v[18:21]
	v_mfma_f32_16x16x32_bf16 v[10:13], v[138:141], v[210:213], v[10:13]
	v_mfma_f32_16x16x32_bf16 v[62:65], v[134:137], v[180:183], v[62:65]
	v_mfma_f32_16x16x32_bf16 v[58:61], v[142:145], v[180:183], v[58:61]
	v_mfma_f32_16x16x32_bf16 v[50:53], v[134:137], v[190:193], v[50:53]
	v_mfma_f32_16x16x32_bf16 v[42:45], v[142:145], v[190:193], v[42:45]
	v_mfma_f32_16x16x32_bf16 v[34:37], v[134:137], v[206:209], v[34:37]
	v_mfma_f32_16x16x32_bf16 v[26:29], v[142:145], v[206:209], v[26:29]
	v_mfma_f32_16x16x32_bf16 v[18:21], v[134:137], v[214:217], v[18:21]
	v_mfma_f32_16x16x32_bf16 v[10:13], v[142:145], v[214:217], v[10:13]
	v_mfma_f32_16x16x32_bf16 v[54:57], v[146:149], v[162:165], v[54:57]
	v_mfma_f32_16x16x32_bf16 v[46:49], v[154:157], v[162:165], v[46:49]
	v_mfma_f32_16x16x32_bf16 v[38:41], v[146:149], v[184:187], v[38:41]
	v_mfma_f32_16x16x32_bf16 v[30:33], v[154:157], v[184:187], v[30:33]
	v_mfma_f32_16x16x32_bf16 v[22:25], v[146:149], v[202:205], v[22:25]
	v_mfma_f32_16x16x32_bf16 v[14:17], v[154:157], v[202:205], v[14:17]
	v_mfma_f32_16x16x32_bf16 v[6:9], v[146:149], v[210:213], v[6:9]
	v_mfma_f32_16x16x32_bf16 v[2:5], v[154:157], v[210:213], v[2:5]
	v_mfma_f32_16x16x32_bf16 v[54:57], v[150:153], v[180:183], v[54:57]
	v_mfma_f32_16x16x32_bf16 v[46:49], v[158:161], v[180:183], v[46:49]
	v_mfma_f32_16x16x32_bf16 v[38:41], v[150:153], v[190:193], v[38:41]
	v_mfma_f32_16x16x32_bf16 v[30:33], v[158:161], v[190:193], v[30:33]
	v_mfma_f32_16x16x32_bf16 v[22:25], v[150:153], v[206:209], v[22:25]
	v_mfma_f32_16x16x32_bf16 v[14:17], v[158:161], v[206:209], v[14:17]
	v_mfma_f32_16x16x32_bf16 v[6:9], v[150:153], v[214:217], v[6:9]
	v_mfma_f32_16x16x32_bf16 v[2:5], v[158:161], v[214:217], v[2:5]
	s_barrier
	s_setprio 0
	s_add_i32 s78, 0, 0x18000
	s_add_i32 s79, 0, 0x1c000
	v_add_u32_e32 v142, s78, v188
	v_add_u32_e32 v158, s79, v188
	ds_read_b128 v[130:133], v142
	ds_read_b128 v[134:137], v142 offset:1024
	ds_read_b128 v[138:141], v142 offset:2048
	ds_read_b128 v[142:145], v142 offset:3072
	ds_read_b128 v[146:149], v158
	ds_read_b128 v[150:153], v158 offset:1024
	ds_read_b128 v[154:157], v158 offset:2048
	ds_read_b128 v[158:161], v158 offset:3072
	s_add_u32 s0, s64, 0x80000
	s_addc_u32 s1, s65, 0
	s_mov_b32 m0, s29
	ds_read_b128 v[162:165], v189 offset:32768
	ds_read_b128 v[180:183], v189 offset:33792
	ds_read_b128 v[184:187], v189 offset:34816
	ds_read_b128 v[190:193], v189 offset:35840
	ds_read_b128 v[202:205], v189 offset:36864
	ds_read_b128 v[206:209], v189 offset:37888
	ds_read_b128 v[210:213], v189 offset:38912
	ds_read_b128 v[214:217], v189 offset:39936
	global_load_lds_dwordx4 v166, s[0:1]
	s_mov_b32 m0, s30
	s_nop 0
	global_load_lds_dwordx4 v168, s[0:1]
	s_waitcnt vmcnt(8)
	s_waitcnt lgkmcnt(0)
	s_setprio 1
	s_barrier
	v_mfma_f32_16x16x32_bf16 v[126:129], v[130:133], v[162:165], v[126:129]
	v_mfma_f32_16x16x32_bf16 v[122:125], v[138:141], v[162:165], v[122:125]
	v_mfma_f32_16x16x32_bf16 v[110:113], v[130:133], v[184:187], v[110:113]
	v_mfma_f32_16x16x32_bf16 v[106:109], v[138:141], v[184:187], v[106:109]
	v_mfma_f32_16x16x32_bf16 v[98:101], v[130:133], v[202:205], v[98:101]
	v_mfma_f32_16x16x32_bf16 v[90:93], v[138:141], v[202:205], v[90:93]
	v_mfma_f32_16x16x32_bf16 v[82:85], v[130:133], v[210:213], v[82:85]
	v_mfma_f32_16x16x32_bf16 v[74:77], v[138:141], v[210:213], v[74:77]
	v_mfma_f32_16x16x32_bf16 v[126:129], v[134:137], v[180:183], v[126:129]
	v_mfma_f32_16x16x32_bf16 v[122:125], v[142:145], v[180:183], v[122:125]
	v_mfma_f32_16x16x32_bf16 v[110:113], v[134:137], v[190:193], v[110:113]
	v_mfma_f32_16x16x32_bf16 v[106:109], v[142:145], v[190:193], v[106:109]
	v_mfma_f32_16x16x32_bf16 v[98:101], v[134:137], v[206:209], v[98:101]
	v_mfma_f32_16x16x32_bf16 v[90:93], v[142:145], v[206:209], v[90:93]
	v_mfma_f32_16x16x32_bf16 v[82:85], v[134:137], v[214:217], v[82:85]
	v_mfma_f32_16x16x32_bf16 v[74:77], v[142:145], v[214:217], v[74:77]
	v_mfma_f32_16x16x32_bf16 v[118:121], v[146:149], v[162:165], v[118:121]
	v_mfma_f32_16x16x32_bf16 v[114:117], v[154:157], v[162:165], v[114:117]
	v_mfma_f32_16x16x32_bf16 v[102:105], v[146:149], v[184:187], v[102:105]
	v_mfma_f32_16x16x32_bf16 v[94:97], v[154:157], v[184:187], v[94:97]
	v_mfma_f32_16x16x32_bf16 v[86:89], v[146:149], v[202:205], v[86:89]
	v_mfma_f32_16x16x32_bf16 v[78:81], v[154:157], v[202:205], v[78:81]
	v_mfma_f32_16x16x32_bf16 v[70:73], v[146:149], v[210:213], v[70:73]
	v_mfma_f32_16x16x32_bf16 v[66:69], v[154:157], v[210:213], v[66:69]
	v_mfma_f32_16x16x32_bf16 v[118:121], v[150:153], v[180:183], v[118:121]
	v_mfma_f32_16x16x32_bf16 v[114:117], v[158:161], v[180:183], v[114:117]
	v_mfma_f32_16x16x32_bf16 v[102:105], v[150:153], v[190:193], v[102:105]
	v_mfma_f32_16x16x32_bf16 v[94:97], v[158:161], v[190:193], v[94:97]
	v_mfma_f32_16x16x32_bf16 v[86:89], v[150:153], v[206:209], v[86:89]
	v_mfma_f32_16x16x32_bf16 v[78:81], v[158:161], v[206:209], v[78:81]
	v_mfma_f32_16x16x32_bf16 v[70:73], v[150:153], v[214:217], v[70:73]
	v_mfma_f32_16x16x32_bf16 v[66:69], v[158:161], v[214:217], v[66:69]
	s_barrier
	s_setprio 0
	s_add_i32 s0, s78, s26
	s_mov_b32 m0, s0
	ds_read_b128 v[162:165], v189 offset:49152
	ds_read_b128 v[180:183], v189 offset:50176
	ds_read_b128 v[184:187], v189 offset:51200
	ds_read_b128 v[190:193], v189 offset:52224
	ds_read_b128 v[202:205], v189 offset:53248
	ds_read_b128 v[206:209], v189 offset:54272
	ds_read_b128 v[210:213], v189 offset:55296
	ds_read_b128 v[214:217], v189 offset:56320
	global_load_lds_dwordx4 v196, s[98:99]
	s_add_i32 m0, s0, 0x2000
	s_add_u32 s0, s8, 0x80080
	s_addc_u32 s1, s9, 0
	s_add_i32 s8, s79, s26
	global_load_lds_dwordx4 v170, s[98:99]
	s_mov_b32 m0, s8
	s_nop 0
	global_load_lds_dwordx4 v196, s[0:1]
	s_add_i32 m0, s8, 0x2000
	s_nop 0
	global_load_lds_dwordx4 v170, s[0:1]
	v_lshl_add_u64 v[194:195], v[220:221], 0, s[16:17]
	s_mov_b32 m0, s35
	s_nop 0
	global_load_lds_dwordx4 v[194:195], off
	v_lshl_add_u64 v[194:195], v[222:223], 0, s[16:17]
	s_mov_b32 m0, s53
	s_nop 0
	global_load_lds_dwordx4 v[194:195], off
	s_waitcnt vmcnt(8)
	s_waitcnt lgkmcnt(0)
	s_setprio 1
	s_barrier
	v_mfma_f32_16x16x32_bf16 v[62:65], v[130:133], v[162:165], v[62:65]
	v_mfma_f32_16x16x32_bf16 v[58:61], v[138:141], v[162:165], v[58:61]
	v_mfma_f32_16x16x32_bf16 v[50:53], v[130:133], v[184:187], v[50:53]
	v_mfma_f32_16x16x32_bf16 v[42:45], v[138:141], v[184:187], v[42:45]
	v_mfma_f32_16x16x32_bf16 v[34:37], v[130:133], v[202:205], v[34:37]
	v_mfma_f32_16x16x32_bf16 v[26:29], v[138:141], v[202:205], v[26:29]
	v_mfma_f32_16x16x32_bf16 v[18:21], v[130:133], v[210:213], v[18:21]
	v_mfma_f32_16x16x32_bf16 v[10:13], v[138:141], v[210:213], v[10:13]
	v_mfma_f32_16x16x32_bf16 v[62:65], v[134:137], v[180:183], v[62:65]
	v_mfma_f32_16x16x32_bf16 v[58:61], v[142:145], v[180:183], v[58:61]
	v_mfma_f32_16x16x32_bf16 v[50:53], v[134:137], v[190:193], v[50:53]
	v_mfma_f32_16x16x32_bf16 v[42:45], v[142:145], v[190:193], v[42:45]
	v_mfma_f32_16x16x32_bf16 v[34:37], v[134:137], v[206:209], v[34:37]
	v_mfma_f32_16x16x32_bf16 v[26:29], v[142:145], v[206:209], v[26:29]
	v_mfma_f32_16x16x32_bf16 v[18:21], v[134:137], v[214:217], v[18:21]
	v_mfma_f32_16x16x32_bf16 v[10:13], v[142:145], v[214:217], v[10:13]
	v_mfma_f32_16x16x32_bf16 v[54:57], v[146:149], v[162:165], v[54:57]
	v_mfma_f32_16x16x32_bf16 v[46:49], v[154:157], v[162:165], v[46:49]
	v_mfma_f32_16x16x32_bf16 v[38:41], v[146:149], v[184:187], v[38:41]
	v_mfma_f32_16x16x32_bf16 v[30:33], v[154:157], v[184:187], v[30:33]
	v_mfma_f32_16x16x32_bf16 v[22:25], v[146:149], v[202:205], v[22:25]
	v_mfma_f32_16x16x32_bf16 v[14:17], v[154:157], v[202:205], v[14:17]
	v_mfma_f32_16x16x32_bf16 v[6:9], v[146:149], v[210:213], v[6:9]
	v_mfma_f32_16x16x32_bf16 v[2:5], v[154:157], v[210:213], v[2:5]
	v_mfma_f32_16x16x32_bf16 v[54:57], v[150:153], v[180:183], v[54:57]
	v_mfma_f32_16x16x32_bf16 v[46:49], v[158:161], v[180:183], v[46:49]
	v_mfma_f32_16x16x32_bf16 v[38:41], v[150:153], v[190:193], v[38:41]
	v_mfma_f32_16x16x32_bf16 v[30:33], v[158:161], v[190:193], v[30:33]
	v_mfma_f32_16x16x32_bf16 v[22:25], v[150:153], v[206:209], v[22:25]
	v_mfma_f32_16x16x32_bf16 v[14:17], v[158:161], v[206:209], v[14:17]
	v_mfma_f32_16x16x32_bf16 v[6:9], v[150:153], v[214:217], v[6:9]
	v_mfma_f32_16x16x32_bf16 v[2:5], v[158:161], v[214:217], v[2:5]
	s_barrier
	s_setprio 0
	s_add_u32 s72, s72, 0x100
	s_addc_u32 s73, s73, 0
	s_add_u32 s62, s62, 0x100
	s_addc_u32 s63, s63, 0
	s_cmp_ge_i32 s77, s69
	s_mov_b32 s8, s77
	s_cbranch_scc0 .LBB0_2357
	s_and_b64 vcc, exec, s[38:39]
	s_cbranch_vccz .LBB0_2360
	s_barrier

.Ldefbar_skip_5:
.LBB0_2507:
	s_add_i32 s69, s8, 2
	s_add_u32 s0, s52, 0xfff80080
	s_addc_u32 s1, s53, -1
	s_add_i32 s70, 0, 0x10000
	s_cmp_eq_u32 s66, s8
	s_cselect_b32 s59, s41, s1
	s_cselect_b32 s58, s45, s0
	s_cselect_b32 s9, s43, s68
	s_cselect_b32 s8, s65, s67
	s_add_i32 s71, 0, 0x14000
	v_add_u32_e32 v156, s70, v141
	v_add_u32_e32 v172, s71, v141
	ds_read_b128 v[144:147], v156
	ds_read_b128 v[148:151], v156 offset:1024
	ds_read_b128 v[152:155], v156 offset:2048
	ds_read_b128 v[156:159], v156 offset:3072
	ds_read_b128 v[160:163], v172
	ds_read_b128 v[164:167], v172 offset:1024
	ds_read_b128 v[168:171], v172 offset:2048
	ds_read_b128 v[172:175], v172 offset:3072
	s_add_i32 m0, s27, 0xc000
	ds_read_b128 v[176:179], v143
	ds_read_b128 v[180:183], v143 offset:1024
	ds_read_b128 v[184:187], v143 offset:2048
	ds_read_b128 v[188:191], v143 offset:3072
	ds_read_b128 v[192:195], v143 offset:4096
	ds_read_b128 v[202:205], v143 offset:5120
	ds_read_b128 v[206:209], v143 offset:6144
	ds_read_b128 v[210:213], v143 offset:7168
	global_load_lds_dwordx4 v138, s[52:53]
	s_add_i32 m0, s27, 0xe000
	s_nop 0
	global_load_lds_dwordx4 v136, s[52:53]
	s_waitcnt vmcnt(8)
	s_waitcnt lgkmcnt(0)
	s_setprio 1
	s_barrier
	v_mfma_f32_16x16x32_bf16 v[126:129], v[144:147], v[176:179], v[126:129]
	v_mfma_f32_16x16x32_bf16 v[118:121], v[152:155], v[176:179], v[118:121]
	v_mfma_f32_16x16x32_bf16 v[110:113], v[144:147], v[184:187], v[110:113]
	v_mfma_f32_16x16x32_bf16 v[102:105], v[152:155], v[184:187], v[102:105]
	v_mfma_f32_16x16x32_bf16 v[94:97], v[144:147], v[192:195], v[94:97]
	v_mfma_f32_16x16x32_bf16 v[86:89], v[152:155], v[192:195], v[86:89]
	v_mfma_f32_16x16x32_bf16 v[78:81], v[144:147], v[206:209], v[78:81]
	v_mfma_f32_16x16x32_bf16 v[70:73], v[152:155], v[206:209], v[70:73]
	v_mfma_f32_16x16x32_bf16 v[126:129], v[148:151], v[180:183], v[126:129]
	v_mfma_f32_16x16x32_bf16 v[118:121], v[156:159], v[180:183], v[118:121]
	v_mfma_f32_16x16x32_bf16 v[110:113], v[148:151], v[188:191], v[110:113]
	v_mfma_f32_16x16x32_bf16 v[102:105], v[156:159], v[188:191], v[102:105]
	v_mfma_f32_16x16x32_bf16 v[94:97], v[148:151], v[202:205], v[94:97]
	v_mfma_f32_16x16x32_bf16 v[86:89], v[156:159], v[202:205], v[86:89]
	v_mfma_f32_16x16x32_bf16 v[78:81], v[148:151], v[210:213], v[78:81]
	v_mfma_f32_16x16x32_bf16 v[70:73], v[156:159], v[210:213], v[70:73]
	v_mfma_f32_16x16x32_bf16 v[122:125], v[160:163], v[176:179], v[122:125]
	v_mfma_f32_16x16x32_bf16 v[114:117], v[168:171], v[176:179], v[114:117]
	v_mfma_f32_16x16x32_bf16 v[106:109], v[160:163], v[184:187], v[106:109]
	v_mfma_f32_16x16x32_bf16 v[98:101], v[168:171], v[184:187], v[98:101]
	v_mfma_f32_16x16x32_bf16 v[90:93], v[160:163], v[192:195], v[90:93]
	v_mfma_f32_16x16x32_bf16 v[82:85], v[168:171], v[192:195], v[82:85]
	v_mfma_f32_16x16x32_bf16 v[74:77], v[160:163], v[206:209], v[74:77]
	v_mfma_f32_16x16x32_bf16 v[66:69], v[168:171], v[206:209], v[66:69]
	v_mfma_f32_16x16x32_bf16 v[122:125], v[164:167], v[180:183], v[122:125]
	v_mfma_f32_16x16x32_bf16 v[114:117], v[172:175], v[180:183], v[114:117]
	v_mfma_f32_16x16x32_bf16 v[106:109], v[164:167], v[188:191], v[106:109]
	v_mfma_f32_16x16x32_bf16 v[98:101], v[172:175], v[188:191], v[98:101]
	v_mfma_f32_16x16x32_bf16 v[90:93], v[164:167], v[202:205], v[90:93]
	v_mfma_f32_16x16x32_bf16 v[82:85], v[172:175], v[202:205], v[82:85]
	v_mfma_f32_16x16x32_bf16 v[74:77], v[164:167], v[210:213], v[74:77]
	v_mfma_f32_16x16x32_bf16 v[66:69], v[172:175], v[210:213], v[66:69]
	s_barrier
	s_setprio 0
	s_add_i32 s0, s70, s26
	s_add_u32 s98, s8, s16
	s_addc_u32 s99, s9, s17
	s_mov_b32 m0, s0
	ds_read_b128 v[176:179], v143 offset:16384
	ds_read_b128 v[180:183], v143 offset:17408
	ds_read_b128 v[184:187], v143 offset:18432
	ds_read_b128 v[188:191], v143 offset:19456
	ds_read_b128 v[192:195], v143 offset:20480
	ds_read_b128 v[202:205], v143 offset:21504
	ds_read_b128 v[206:209], v143 offset:22528
	ds_read_b128 v[210:213], v143 offset:23552
	global_load_lds_dwordx4 v196, s[8:9]
	s_add_i32 m0, s0, 0x2000
	s_add_u32 s0, s8, 0x80000
	s_addc_u32 s1, s9, 0
	s_add_i32 s70, s71, s26
	global_load_lds_dwordx4 v130, s[8:9]
	s_mov_b32 m0, s70
	s_nop 0
	global_load_lds_dwordx4 v196, s[0:1]
	s_add_i32 m0, s70, 0x2000
	s_nop 0
	global_load_lds_dwordx4 v130, s[0:1]
	s_add_u32 s78, s58, s16
	s_addc_u32 s79, s59, s17
	s_mov_b32 m0, s27
	s_nop 0
	global_load_lds_dwordx4 v134, s[58:59]
	s_mov_b32 m0, s28
	s_nop 0
	global_load_lds_dwordx4 v132, s[58:59]
	s_waitcnt vmcnt(8)
	s_waitcnt lgkmcnt(0)
	s_setprio 1
	s_barrier
	v_mfma_f32_16x16x32_bf16 v[62:65], v[144:147], v[176:179], v[62:65]
	v_mfma_f32_16x16x32_bf16 v[54:57], v[152:155], v[176:179], v[54:57]
	v_mfma_f32_16x16x32_bf16 v[46:49], v[144:147], v[184:187], v[46:49]
	v_mfma_f32_16x16x32_bf16 v[38:41], v[152:155], v[184:187], v[38:41]
	v_mfma_f32_16x16x32_bf16 v[30:33], v[144:147], v[192:195], v[30:33]
	v_mfma_f32_16x16x32_bf16 v[22:25], v[152:155], v[192:195], v[22:25]
	v_mfma_f32_16x16x32_bf16 v[14:17], v[144:147], v[206:209], v[14:17]
	v_mfma_f32_16x16x32_bf16 v[6:9], v[152:155], v[206:209], v[6:9]
	v_mfma_f32_16x16x32_bf16 v[62:65], v[148:151], v[180:183], v[62:65]
	v_mfma_f32_16x16x32_bf16 v[54:57], v[156:159], v[180:183], v[54:57]
	v_mfma_f32_16x16x32_bf16 v[46:49], v[148:151], v[188:191], v[46:49]
	v_mfma_f32_16x16x32_bf16 v[38:41], v[156:159], v[188:191], v[38:41]
	v_mfma_f32_16x16x32_bf16 v[30:33], v[148:151], v[202:205], v[30:33]
	v_mfma_f32_16x16x32_bf16 v[22:25], v[156:159], v[202:205], v[22:25]
	v_mfma_f32_16x16x32_bf16 v[14:17], v[148:151], v[210:213], v[14:17]
	v_mfma_f32_16x16x32_bf16 v[6:9], v[156:159], v[210:213], v[6:9]
	v_mfma_f32_16x16x32_bf16 v[58:61], v[160:163], v[176:179], v[58:61]
	v_mfma_f32_16x16x32_bf16 v[50:53], v[168:171], v[176:179], v[50:53]
	v_mfma_f32_16x16x32_bf16 v[42:45], v[160:163], v[184:187], v[42:45]
	v_mfma_f32_16x16x32_bf16 v[34:37], v[168:171], v[184:187], v[34:37]
	v_mfma_f32_16x16x32_bf16 v[26:29], v[160:163], v[192:195], v[26:29]
	v_mfma_f32_16x16x32_bf16 v[18:21], v[168:171], v[192:195], v[18:21]
	v_mfma_f32_16x16x32_bf16 v[10:13], v[160:163], v[206:209], v[10:13]
	v_mfma_f32_16x16x32_bf16 v[2:5], v[168:171], v[206:209], v[2:5]
	v_mfma_f32_16x16x32_bf16 v[58:61], v[164:167], v[180:183], v[58:61]
	v_mfma_f32_16x16x32_bf16 v[50:53], v[172:175], v[180:183], v[50:53]
	v_mfma_f32_16x16x32_bf16 v[42:45], v[164:167], v[188:191], v[42:45]
	v_mfma_f32_16x16x32_bf16 v[34:37], v[172:175], v[188:191], v[34:37]
	v_mfma_f32_16x16x32_bf16 v[26:29], v[164:167], v[202:205], v[26:29]
	v_mfma_f32_16x16x32_bf16 v[18:21], v[172:175], v[202:205], v[18:21]
	v_mfma_f32_16x16x32_bf16 v[10:13], v[164:167], v[210:213], v[10:13]
	v_mfma_f32_16x16x32_bf16 v[2:5], v[172:175], v[210:213], v[2:5]
	s_barrier
	s_setprio 0
	s_add_i32 s70, 0, 0x18000
	s_add_i32 s71, 0, 0x1c000
	v_add_u32_e32 v156, s70, v141
	v_add_u32_e32 v172, s71, v141
	ds_read_b128 v[144:147], v156
	ds_read_b128 v[148:151], v156 offset:1024
	ds_read_b128 v[152:155], v156 offset:2048
	ds_read_b128 v[156:159], v156 offset:3072
	ds_read_b128 v[160:163], v172
	ds_read_b128 v[164:167], v172 offset:1024
	ds_read_b128 v[168:171], v172 offset:2048
	ds_read_b128 v[172:175], v172 offset:3072
	s_add_u32 s0, s58, 0x80000
	s_addc_u32 s1, s59, 0
	s_mov_b32 m0, s29
	ds_read_b128 v[176:179], v143 offset:32768
	ds_read_b128 v[180:183], v143 offset:33792
	ds_read_b128 v[184:187], v143 offset:34816
	ds_read_b128 v[188:191], v143 offset:35840
	ds_read_b128 v[192:195], v143 offset:36864
	ds_read_b128 v[202:205], v143 offset:37888
	ds_read_b128 v[206:209], v143 offset:38912
	ds_read_b128 v[210:213], v143 offset:39936
	global_load_lds_dwordx4 v134, s[0:1]
	s_mov_b32 m0, s30
	s_nop 0
	global_load_lds_dwordx4 v132, s[0:1]
	s_waitcnt vmcnt(8)
	s_waitcnt lgkmcnt(0)
	s_setprio 1
	s_barrier
	v_mfma_f32_16x16x32_bf16 v[126:129], v[144:147], v[176:179], v[126:129]
	v_mfma_f32_16x16x32_bf16 v[118:121], v[152:155], v[176:179], v[118:121]
	v_mfma_f32_16x16x32_bf16 v[110:113], v[144:147], v[184:187], v[110:113]
	v_mfma_f32_16x16x32_bf16 v[102:105], v[152:155], v[184:187], v[102:105]
	v_mfma_f32_16x16x32_bf16 v[94:97], v[144:147], v[192:195], v[94:97]
	v_mfma_f32_16x16x32_bf16 v[86:89], v[152:155], v[192:195], v[86:89]
	v_mfma_f32_16x16x32_bf16 v[78:81], v[144:147], v[206:209], v[78:81]
	v_mfma_f32_16x16x32_bf16 v[70:73], v[152:155], v[206:209], v[70:73]
	v_mfma_f32_16x16x32_bf16 v[126:129], v[148:151], v[180:183], v[126:129]
	v_mfma_f32_16x16x32_bf16 v[118:121], v[156:159], v[180:183], v[118:121]
	v_mfma_f32_16x16x32_bf16 v[110:113], v[148:151], v[188:191], v[110:113]
	v_mfma_f32_16x16x32_bf16 v[102:105], v[156:159], v[188:191], v[102:105]
	v_mfma_f32_16x16x32_bf16 v[94:97], v[148:151], v[202:205], v[94:97]
	v_mfma_f32_16x16x32_bf16 v[86:89], v[156:159], v[202:205], v[86:89]
	v_mfma_f32_16x16x32_bf16 v[78:81], v[148:151], v[210:213], v[78:81]
	v_mfma_f32_16x16x32_bf16 v[70:73], v[156:159], v[210:213], v[70:73]
	v_mfma_f32_16x16x32_bf16 v[122:125], v[160:163], v[176:179], v[122:125]
	v_mfma_f32_16x16x32_bf16 v[114:117], v[168:171], v[176:179], v[114:117]
	v_mfma_f32_16x16x32_bf16 v[106:109], v[160:163], v[184:187], v[106:109]
	v_mfma_f32_16x16x32_bf16 v[98:101], v[168:171], v[184:187], v[98:101]
	v_mfma_f32_16x16x32_bf16 v[90:93], v[160:163], v[192:195], v[90:93]
	v_mfma_f32_16x16x32_bf16 v[82:85], v[168:171], v[192:195], v[82:85]
	v_mfma_f32_16x16x32_bf16 v[74:77], v[160:163], v[206:209], v[74:77]
	v_mfma_f32_16x16x32_bf16 v[66:69], v[168:171], v[206:209], v[66:69]
	v_mfma_f32_16x16x32_bf16 v[122:125], v[164:167], v[180:183], v[122:125]
	v_mfma_f32_16x16x32_bf16 v[114:117], v[172:175], v[180:183], v[114:117]
	v_mfma_f32_16x16x32_bf16 v[106:109], v[164:167], v[188:191], v[106:109]
	v_mfma_f32_16x16x32_bf16 v[98:101], v[172:175], v[188:191], v[98:101]
	v_mfma_f32_16x16x32_bf16 v[90:93], v[164:167], v[202:205], v[90:93]
	v_mfma_f32_16x16x32_bf16 v[82:85], v[172:175], v[202:205], v[82:85]
	v_mfma_f32_16x16x32_bf16 v[74:77], v[164:167], v[210:213], v[74:77]
	v_mfma_f32_16x16x32_bf16 v[66:69], v[172:175], v[210:213], v[66:69]
	s_barrier
	s_setprio 0
	s_add_i32 s0, s70, s26
	s_mov_b32 m0, s0
	ds_read_b128 v[176:179], v143 offset:49152
	ds_read_b128 v[180:183], v143 offset:50176
	ds_read_b128 v[184:187], v143 offset:51200
	ds_read_b128 v[188:191], v143 offset:52224
	ds_read_b128 v[192:195], v143 offset:53248
	ds_read_b128 v[202:205], v143 offset:54272
	ds_read_b128 v[206:209], v143 offset:55296
	ds_read_b128 v[210:213], v143 offset:56320
	global_load_lds_dwordx4 v196, s[98:99]
	s_add_i32 m0, s0, 0x2000
	s_add_u32 s0, s8, 0x80080
	s_addc_u32 s1, s9, 0
	s_add_i32 s8, s71, s26
	global_load_lds_dwordx4 v130, s[98:99]
	s_mov_b32 m0, s8
	s_nop 0
	global_load_lds_dwordx4 v196, s[0:1]
	s_add_i32 m0, s8, 0x2000
	s_nop 0
	global_load_lds_dwordx4 v130, s[0:1]
	s_mov_b32 m0, s31
	s_nop 0
	global_load_lds_dwordx4 v134, s[78:79]
	s_mov_b32 m0, s34
	s_nop 0
	global_load_lds_dwordx4 v132, s[78:79]
	s_waitcnt vmcnt(8)
	s_waitcnt lgkmcnt(0)
	s_setprio 1
	s_barrier
	v_mfma_f32_16x16x32_bf16 v[62:65], v[144:147], v[176:179], v[62:65]
	v_mfma_f32_16x16x32_bf16 v[54:57], v[152:155], v[176:179], v[54:57]
	v_mfma_f32_16x16x32_bf16 v[46:49], v[144:147], v[184:187], v[46:49]
	v_mfma_f32_16x16x32_bf16 v[38:41], v[152:155], v[184:187], v[38:41]
	v_mfma_f32_16x16x32_bf16 v[30:33], v[144:147], v[192:195], v[30:33]
	v_mfma_f32_16x16x32_bf16 v[22:25], v[152:155], v[192:195], v[22:25]
	v_mfma_f32_16x16x32_bf16 v[14:17], v[144:147], v[206:209], v[14:17]
	v_mfma_f32_16x16x32_bf16 v[6:9], v[152:155], v[206:209], v[6:9]
	v_mfma_f32_16x16x32_bf16 v[62:65], v[148:151], v[180:183], v[62:65]
	v_mfma_f32_16x16x32_bf16 v[54:57], v[156:159], v[180:183], v[54:57]
	v_mfma_f32_16x16x32_bf16 v[46:49], v[148:151], v[188:191], v[46:49]
	v_mfma_f32_16x16x32_bf16 v[38:41], v[156:159], v[188:191], v[38:41]
	v_mfma_f32_16x16x32_bf16 v[30:33], v[148:151], v[202:205], v[30:33]
	v_mfma_f32_16x16x32_bf16 v[22:25], v[156:159], v[202:205], v[22:25]
	v_mfma_f32_16x16x32_bf16 v[14:17], v[148:151], v[210:213], v[14:17]
	v_mfma_f32_16x16x32_bf16 v[6:9], v[156:159], v[210:213], v[6:9]
	v_mfma_f32_16x16x32_bf16 v[58:61], v[160:163], v[176:179], v[58:61]
	v_mfma_f32_16x16x32_bf16 v[50:53], v[168:171], v[176:179], v[50:53]
	v_mfma_f32_16x16x32_bf16 v[42:45], v[160:163], v[184:187], v[42:45]
	v_mfma_f32_16x16x32_bf16 v[34:37], v[168:171], v[184:187], v[34:37]
	v_mfma_f32_16x16x32_bf16 v[26:29], v[160:163], v[192:195], v[26:29]
	v_mfma_f32_16x16x32_bf16 v[18:21], v[168:171], v[192:195], v[18:21]
	v_mfma_f32_16x16x32_bf16 v[10:13], v[160:163], v[206:209], v[10:13]
	v_mfma_f32_16x16x32_bf16 v[2:5], v[168:171], v[206:209], v[2:5]
	v_mfma_f32_16x16x32_bf16 v[58:61], v[164:167], v[180:183], v[58:61]
	v_mfma_f32_16x16x32_bf16 v[50:53], v[172:175], v[180:183], v[50:53]
	v_mfma_f32_16x16x32_bf16 v[42:45], v[164:167], v[188:191], v[42:45]
	v_mfma_f32_16x16x32_bf16 v[34:37], v[172:175], v[188:191], v[34:37]
	v_mfma_f32_16x16x32_bf16 v[26:29], v[164:167], v[202:205], v[26:29]
	v_mfma_f32_16x16x32_bf16 v[18:21], v[172:175], v[202:205], v[18:21]
	v_mfma_f32_16x16x32_bf16 v[10:13], v[164:167], v[210:213], v[10:13]
	v_mfma_f32_16x16x32_bf16 v[2:5], v[172:175], v[210:213], v[2:5]
	s_barrier
	s_setprio 0
	s_add_u32 s67, s67, 0x100
	s_addc_u32 s68, s68, 0
	s_add_u32 s52, s52, 0x100
	s_addc_u32 s53, s53, 0
	s_cmp_ge_i32 s69, s62
	s_mov_b32 s8, s69
	s_cbranch_scc0 .LBB0_2507
	s_and_b64 vcc, exec, s[38:39]
	s_cbranch_vccz .LBB0_2510
	s_barrier

.Ldefbar_skip_6:
.LBB0_2588:
	s_add_i32 s72, s48, 2
	s_add_u32 s8, s46, 0x100
	s_addc_u32 s9, s47, 0
	s_add_i32 s0, 0, 0x10000
	s_cmp_eq_u32 s41, s48
	s_cselect_b32 s51, s43, s9
	s_cselect_b32 s50, s42, s8
	s_cselect_b32 s49, s45, s71
	s_cselect_b32 s48, s44, s70
	s_add_i32 s73, 0, 0x14000
	v_add_u32_e32 v142, s0, v188
	v_add_u32_e32 v172, s73, v188
	ds_read_b128 v[130:133], v142
	ds_read_b128 v[134:137], v142 offset:1024
	ds_read_b128 v[138:141], v142 offset:2048
	ds_read_b128 v[142:145], v142 offset:3072
	ds_read_b128 v[146:149], v172
	ds_read_b128 v[164:167], v172 offset:1024
	ds_read_b128 v[168:171], v172 offset:2048
	ds_read_b128 v[172:175], v172 offset:3072
	v_lshl_add_u64 v[194:195], s[46:47], 0, v[162:163]
	s_add_i32 m0, s27, 0xc000
	ds_read_b128 v[176:179], v189
	ds_read_b128 v[180:183], v189 offset:1024
	ds_read_b128 v[184:187], v189 offset:2048
	ds_read_b128 v[190:193], v189 offset:3072
	ds_read_b128 v[202:205], v189 offset:4096
	ds_read_b128 v[206:209], v189 offset:5120
	ds_read_b128 v[210:213], v189 offset:6144
	ds_read_b128 v[214:217], v189 offset:7168
	global_load_lds_dwordx4 v[194:195], off
	v_lshl_add_u64 v[194:195], s[46:47], 0, v[160:161]
	s_add_i32 m0, s27, 0xe000
	s_nop 0
	global_load_lds_dwordx4 v[194:195], off
	s_waitcnt vmcnt(8)
	s_waitcnt lgkmcnt(0)
	s_setprio 1
	s_barrier
	v_mfma_f32_16x16x32_bf16 v[126:129], v[130:133], v[176:179], v[126:129]
	v_mfma_f32_16x16x32_bf16 v[122:125], v[138:141], v[176:179], v[122:125]
	v_mfma_f32_16x16x32_bf16 v[110:113], v[130:133], v[184:187], v[110:113]
	v_mfma_f32_16x16x32_bf16 v[106:109], v[138:141], v[184:187], v[106:109]
	v_mfma_f32_16x16x32_bf16 v[98:101], v[130:133], v[202:205], v[98:101]
	v_mfma_f32_16x16x32_bf16 v[90:93], v[138:141], v[202:205], v[90:93]
	v_mfma_f32_16x16x32_bf16 v[82:85], v[130:133], v[210:213], v[82:85]
	v_mfma_f32_16x16x32_bf16 v[74:77], v[138:141], v[210:213], v[74:77]
	v_mfma_f32_16x16x32_bf16 v[126:129], v[134:137], v[180:183], v[126:129]
	v_mfma_f32_16x16x32_bf16 v[122:125], v[142:145], v[180:183], v[122:125]
	v_mfma_f32_16x16x32_bf16 v[110:113], v[134:137], v[190:193], v[110:113]
	v_mfma_f32_16x16x32_bf16 v[106:109], v[142:145], v[190:193], v[106:109]
	v_mfma_f32_16x16x32_bf16 v[98:101], v[134:137], v[206:209], v[98:101]
	v_mfma_f32_16x16x32_bf16 v[90:93], v[142:145], v[206:209], v[90:93]
	v_mfma_f32_16x16x32_bf16 v[82:85], v[134:137], v[214:217], v[82:85]
	v_mfma_f32_16x16x32_bf16 v[74:77], v[142:145], v[214:217], v[74:77]
	v_mfma_f32_16x16x32_bf16 v[118:121], v[146:149], v[176:179], v[118:121]
	v_mfma_f32_16x16x32_bf16 v[114:117], v[168:171], v[176:179], v[114:117]
	v_mfma_f32_16x16x32_bf16 v[102:105], v[146:149], v[184:187], v[102:105]
	v_mfma_f32_16x16x32_bf16 v[94:97], v[168:171], v[184:187], v[94:97]
	v_mfma_f32_16x16x32_bf16 v[86:89], v[146:149], v[202:205], v[86:89]
	v_mfma_f32_16x16x32_bf16 v[78:81], v[168:171], v[202:205], v[78:81]
	v_mfma_f32_16x16x32_bf16 v[70:73], v[146:149], v[210:213], v[70:73]
	v_mfma_f32_16x16x32_bf16 v[66:69], v[168:171], v[210:213], v[66:69]
	v_mfma_f32_16x16x32_bf16 v[118:121], v[164:167], v[180:183], v[118:121]
	v_mfma_f32_16x16x32_bf16 v[114:117], v[172:175], v[180:183], v[114:117]
	v_mfma_f32_16x16x32_bf16 v[102:105], v[164:167], v[190:193], v[102:105]
	v_mfma_f32_16x16x32_bf16 v[94:97], v[172:175], v[190:193], v[94:97]
	v_mfma_f32_16x16x32_bf16 v[86:89], v[164:167], v[206:209], v[86:89]
	v_mfma_f32_16x16x32_bf16 v[78:81], v[172:175], v[206:209], v[78:81]
	v_mfma_f32_16x16x32_bf16 v[70:73], v[164:167], v[214:217], v[70:73]
	v_mfma_f32_16x16x32_bf16 v[66:69], v[172:175], v[214:217], v[66:69]
	s_barrier
	s_setprio 0
	s_add_i32 s0, s0, s26
	s_add_u32 s98, s48, s16
	s_addc_u32 s99, s49, s17
	s_mov_b32 m0, s0
	ds_read_b128 v[176:179], v189 offset:16384
	ds_read_b128 v[180:183], v189 offset:17408
	ds_read_b128 v[184:187], v189 offset:18432
	ds_read_b128 v[190:193], v189 offset:19456
	ds_read_b128 v[202:205], v189 offset:20480
	ds_read_b128 v[206:209], v189 offset:21504
	ds_read_b128 v[210:213], v189 offset:22528
	ds_read_b128 v[214:217], v189 offset:23552
	global_load_lds_dwordx4 v196, s[48:49]
	s_add_i32 m0, s0, 0x2000
	s_add_u32 s0, s48, 0x158000
	s_addc_u32 s1, s49, 0
	s_add_i32 s46, s73, s26
	global_load_lds_dwordx4 v154, s[48:49]
	s_mov_b32 m0, s46
	s_nop 0
	global_load_lds_dwordx4 v196, s[0:1]
	s_add_i32 m0, s46, 0x2000
	s_nop 0
	global_load_lds_dwordx4 v154, s[0:1]
	s_add_u32 s78, s50, s16
	s_addc_u32 s79, s51, s17
	s_mov_b32 m0, s27
	s_nop 0
	global_load_lds_dwordx4 v150, s[50:51]
	s_mov_b32 m0, s30
	s_nop 0
	global_load_lds_dwordx4 v152, s[50:51]
	s_waitcnt vmcnt(8)
	s_waitcnt lgkmcnt(0)
	s_setprio 1
	s_barrier
	v_mfma_f32_16x16x32_bf16 v[62:65], v[130:133], v[176:179], v[62:65]
	v_mfma_f32_16x16x32_bf16 v[58:61], v[138:141], v[176:179], v[58:61]
	v_mfma_f32_16x16x32_bf16 v[50:53], v[130:133], v[184:187], v[50:53]
	v_mfma_f32_16x16x32_bf16 v[42:45], v[138:141], v[184:187], v[42:45]
	v_mfma_f32_16x16x32_bf16 v[34:37], v[130:133], v[202:205], v[34:37]
	v_mfma_f32_16x16x32_bf16 v[26:29], v[138:141], v[202:205], v[26:29]
	v_mfma_f32_16x16x32_bf16 v[18:21], v[130:133], v[210:213], v[18:21]
	v_mfma_f32_16x16x32_bf16 v[10:13], v[138:141], v[210:213], v[10:13]
	v_mfma_f32_16x16x32_bf16 v[62:65], v[134:137], v[180:183], v[62:65]
	v_mfma_f32_16x16x32_bf16 v[58:61], v[142:145], v[180:183], v[58:61]
	v_mfma_f32_16x16x32_bf16 v[50:53], v[134:137], v[190:193], v[50:53]
	v_mfma_f32_16x16x32_bf16 v[42:45], v[142:145], v[190:193], v[42:45]
	v_mfma_f32_16x16x32_bf16 v[34:37], v[134:137], v[206:209], v[34:37]
	v_mfma_f32_16x16x32_bf16 v[26:29], v[142:145], v[206:209], v[26:29]
	v_mfma_f32_16x16x32_bf16 v[18:21], v[134:137], v[214:217], v[18:21]
	v_mfma_f32_16x16x32_bf16 v[10:13], v[142:145], v[214:217], v[10:13]
	v_mfma_f32_16x16x32_bf16 v[54:57], v[146:149], v[176:179], v[54:57]
	v_mfma_f32_16x16x32_bf16 v[46:49], v[168:171], v[176:179], v[46:49]
	v_mfma_f32_16x16x32_bf16 v[38:41], v[146:149], v[184:187], v[38:41]
	v_mfma_f32_16x16x32_bf16 v[30:33], v[168:171], v[184:187], v[30:33]
	v_mfma_f32_16x16x32_bf16 v[22:25], v[146:149], v[202:205], v[22:25]
	v_mfma_f32_16x16x32_bf16 v[14:17], v[168:171], v[202:205], v[14:17]
	v_mfma_f32_16x16x32_bf16 v[6:9], v[146:149], v[210:213], v[6:9]
	v_mfma_f32_16x16x32_bf16 v[2:5], v[168:171], v[210:213], v[2:5]
	v_mfma_f32_16x16x32_bf16 v[54:57], v[164:167], v[180:183], v[54:57]
	v_mfma_f32_16x16x32_bf16 v[46:49], v[172:175], v[180:183], v[46:49]
	v_mfma_f32_16x16x32_bf16 v[38:41], v[164:167], v[190:193], v[38:41]
	v_mfma_f32_16x16x32_bf16 v[30:33], v[172:175], v[190:193], v[30:33]
	v_mfma_f32_16x16x32_bf16 v[22:25], v[164:167], v[206:209], v[22:25]
	v_mfma_f32_16x16x32_bf16 v[14:17], v[172:175], v[206:209], v[14:17]
	v_mfma_f32_16x16x32_bf16 v[6:9], v[164:167], v[214:217], v[6:9]
	v_mfma_f32_16x16x32_bf16 v[2:5], v[172:175], v[214:217], v[2:5]
	s_barrier
	s_setprio 0
	s_add_i32 s46, 0, 0x18000
	s_add_i32 s47, 0, 0x1c000
	v_add_u32_e32 v142, s46, v188
	v_add_u32_e32 v172, s47, v188
	ds_read_b128 v[130:133], v142
	ds_read_b128 v[134:137], v142 offset:1024
	ds_read_b128 v[138:141], v142 offset:2048
	ds_read_b128 v[142:145], v142 offset:3072
	ds_read_b128 v[146:149], v172
	ds_read_b128 v[164:167], v172 offset:1024
	ds_read_b128 v[168:171], v172 offset:2048
	ds_read_b128 v[172:175], v172 offset:3072
	s_add_u32 s0, s50, 0x158000
	s_addc_u32 s1, s51, 0
	s_mov_b32 m0, s31
	ds_read_b128 v[176:179], v189 offset:32768
	ds_read_b128 v[180:183], v189 offset:33792
	ds_read_b128 v[184:187], v189 offset:34816
	ds_read_b128 v[190:193], v189 offset:35840
	ds_read_b128 v[202:205], v189 offset:36864
	ds_read_b128 v[206:209], v189 offset:37888
	ds_read_b128 v[210:213], v189 offset:38912
	ds_read_b128 v[214:217], v189 offset:39936
	global_load_lds_dwordx4 v150, s[0:1]
	s_mov_b32 m0, s34
	s_nop 0
	global_load_lds_dwordx4 v152, s[0:1]
	s_waitcnt vmcnt(8)
	s_waitcnt lgkmcnt(0)
	s_setprio 1
	s_barrier
	v_mfma_f32_16x16x32_bf16 v[126:129], v[130:133], v[176:179], v[126:129]
	v_mfma_f32_16x16x32_bf16 v[122:125], v[138:141], v[176:179], v[122:125]
	v_mfma_f32_16x16x32_bf16 v[110:113], v[130:133], v[184:187], v[110:113]
	v_mfma_f32_16x16x32_bf16 v[106:109], v[138:141], v[184:187], v[106:109]
	v_mfma_f32_16x16x32_bf16 v[98:101], v[130:133], v[202:205], v[98:101]
	v_mfma_f32_16x16x32_bf16 v[90:93], v[138:141], v[202:205], v[90:93]
	v_mfma_f32_16x16x32_bf16 v[82:85], v[130:133], v[210:213], v[82:85]
	v_mfma_f32_16x16x32_bf16 v[74:77], v[138:141], v[210:213], v[74:77]
	v_mfma_f32_16x16x32_bf16 v[126:129], v[134:137], v[180:183], v[126:129]
	v_mfma_f32_16x16x32_bf16 v[122:125], v[142:145], v[180:183], v[122:125]
	v_mfma_f32_16x16x32_bf16 v[110:113], v[134:137], v[190:193], v[110:113]
	v_mfma_f32_16x16x32_bf16 v[106:109], v[142:145], v[190:193], v[106:109]
	v_mfma_f32_16x16x32_bf16 v[98:101], v[134:137], v[206:209], v[98:101]
	v_mfma_f32_16x16x32_bf16 v[90:93], v[142:145], v[206:209], v[90:93]
	v_mfma_f32_16x16x32_bf16 v[82:85], v[134:137], v[214:217], v[82:85]
	v_mfma_f32_16x16x32_bf16 v[74:77], v[142:145], v[214:217], v[74:77]
	v_mfma_f32_16x16x32_bf16 v[118:121], v[146:149], v[176:179], v[118:121]
	v_mfma_f32_16x16x32_bf16 v[114:117], v[168:171], v[176:179], v[114:117]
	v_mfma_f32_16x16x32_bf16 v[102:105], v[146:149], v[184:187], v[102:105]
	v_mfma_f32_16x16x32_bf16 v[94:97], v[168:171], v[184:187], v[94:97]
	v_mfma_f32_16x16x32_bf16 v[86:89], v[146:149], v[202:205], v[86:89]
	v_mfma_f32_16x16x32_bf16 v[78:81], v[168:171], v[202:205], v[78:81]
	v_mfma_f32_16x16x32_bf16 v[70:73], v[146:149], v[210:213], v[70:73]
	v_mfma_f32_16x16x32_bf16 v[66:69], v[168:171], v[210:213], v[66:69]
	v_mfma_f32_16x16x32_bf16 v[118:121], v[164:167], v[180:183], v[118:121]
	v_mfma_f32_16x16x32_bf16 v[114:117], v[172:175], v[180:183], v[114:117]
	v_mfma_f32_16x16x32_bf16 v[102:105], v[164:167], v[190:193], v[102:105]
	v_mfma_f32_16x16x32_bf16 v[94:97], v[172:175], v[190:193], v[94:97]
	v_mfma_f32_16x16x32_bf16 v[86:89], v[164:167], v[206:209], v[86:89]
	v_mfma_f32_16x16x32_bf16 v[78:81], v[172:175], v[206:209], v[78:81]
	v_mfma_f32_16x16x32_bf16 v[70:73], v[164:167], v[214:217], v[70:73]
	v_mfma_f32_16x16x32_bf16 v[66:69], v[172:175], v[214:217], v[66:69]
	s_barrier
	s_setprio 0
	s_add_i32 s0, s46, s26
	s_mov_b32 m0, s0
	ds_read_b128 v[176:179], v189 offset:49152
	ds_read_b128 v[180:183], v189 offset:50176
	ds_read_b128 v[184:187], v189 offset:51200
	ds_read_b128 v[190:193], v189 offset:52224
	ds_read_b128 v[202:205], v189 offset:53248
	ds_read_b128 v[206:209], v189 offset:54272
	ds_read_b128 v[210:213], v189 offset:55296
	ds_read_b128 v[214:217], v189 offset:56320
	global_load_lds_dwordx4 v196, s[98:99]
	s_add_i32 m0, s0, 0x2000
	s_add_u32 s0, s48, 0x158080
	s_addc_u32 s1, s49, 0
	s_add_i32 s46, s47, s26
	global_load_lds_dwordx4 v154, s[98:99]
	s_mov_b32 m0, s46
	s_nop 0
	global_load_lds_dwordx4 v196, s[0:1]
	s_add_i32 m0, s46, 0x2000
	s_nop 0
	global_load_lds_dwordx4 v154, s[0:1]
	s_mov_b32 m0, s53
	s_nop 0
	global_load_lds_dwordx4 v150, s[78:79]
	s_mov_b32 m0, s58
	s_nop 0
	global_load_lds_dwordx4 v152, s[78:79]
	s_waitcnt vmcnt(8)
	s_waitcnt lgkmcnt(0)
	s_setprio 1
	s_barrier
	v_mfma_f32_16x16x32_bf16 v[62:65], v[130:133], v[176:179], v[62:65]
	v_mfma_f32_16x16x32_bf16 v[58:61], v[138:141], v[176:179], v[58:61]
	v_mfma_f32_16x16x32_bf16 v[50:53], v[130:133], v[184:187], v[50:53]
	v_mfma_f32_16x16x32_bf16 v[42:45], v[138:141], v[184:187], v[42:45]
	v_mfma_f32_16x16x32_bf16 v[34:37], v[130:133], v[202:205], v[34:37]
	v_mfma_f32_16x16x32_bf16 v[26:29], v[138:141], v[202:205], v[26:29]
	v_mfma_f32_16x16x32_bf16 v[18:21], v[130:133], v[210:213], v[18:21]
	v_mfma_f32_16x16x32_bf16 v[10:13], v[138:141], v[210:213], v[10:13]
	v_mfma_f32_16x16x32_bf16 v[62:65], v[134:137], v[180:183], v[62:65]
	v_mfma_f32_16x16x32_bf16 v[58:61], v[142:145], v[180:183], v[58:61]
	v_mfma_f32_16x16x32_bf16 v[50:53], v[134:137], v[190:193], v[50:53]
	v_mfma_f32_16x16x32_bf16 v[42:45], v[142:145], v[190:193], v[42:45]
	v_mfma_f32_16x16x32_bf16 v[34:37], v[134:137], v[206:209], v[34:37]
	v_mfma_f32_16x16x32_bf16 v[26:29], v[142:145], v[206:209], v[26:29]
	v_mfma_f32_16x16x32_bf16 v[18:21], v[134:137], v[214:217], v[18:21]
	v_mfma_f32_16x16x32_bf16 v[10:13], v[142:145], v[214:217], v[10:13]
	v_mfma_f32_16x16x32_bf16 v[54:57], v[146:149], v[176:179], v[54:57]
	v_mfma_f32_16x16x32_bf16 v[46:49], v[168:171], v[176:179], v[46:49]
	v_mfma_f32_16x16x32_bf16 v[38:41], v[146:149], v[184:187], v[38:41]
	v_mfma_f32_16x16x32_bf16 v[30:33], v[168:171], v[184:187], v[30:33]
	v_mfma_f32_16x16x32_bf16 v[22:25], v[146:149], v[202:205], v[22:25]
	v_mfma_f32_16x16x32_bf16 v[14:17], v[168:171], v[202:205], v[14:17]
	v_mfma_f32_16x16x32_bf16 v[6:9], v[146:149], v[210:213], v[6:9]
	v_mfma_f32_16x16x32_bf16 v[2:5], v[168:171], v[210:213], v[2:5]
	v_mfma_f32_16x16x32_bf16 v[54:57], v[164:167], v[180:183], v[54:57]
	v_mfma_f32_16x16x32_bf16 v[46:49], v[172:175], v[180:183], v[46:49]
	v_mfma_f32_16x16x32_bf16 v[38:41], v[164:167], v[190:193], v[38:41]
	v_mfma_f32_16x16x32_bf16 v[30:33], v[172:175], v[190:193], v[30:33]
	v_mfma_f32_16x16x32_bf16 v[22:25], v[164:167], v[206:209], v[22:25]
	v_mfma_f32_16x16x32_bf16 v[14:17], v[172:175], v[206:209], v[14:17]
	v_mfma_f32_16x16x32_bf16 v[6:9], v[164:167], v[214:217], v[6:9]
	v_mfma_f32_16x16x32_bf16 v[2:5], v[172:175], v[214:217], v[2:5]
	s_barrier
	s_setprio 0
	s_add_u32 s70, s70, 0x100
	s_addc_u32 s71, s71, 0
	s_cmp_ge_i32 s72, s69
	s_mov_b64 s[46:47], s[8:9]
	s_mov_b32 s48, s72
	s_cbranch_scc0 .LBB0_2588
	s_and_b64 vcc, exec, s[28:29]
	s_cbranch_vccz .LBB0_2591
	s_barrier
